# merge_row wave sums via permlane/DPP; hand-written prenorm0 with all row loads up front
# speedup vs baseline: 1.0813x; 1.0037x over previous
.LBB0_386:
	s_or_b64 exec, exec, s[0:1]
	s_load_dwordx4 s[0:3], s[88:89], 0x178
	v_and_b32_e32 v181, 0xff, v167
	s_mov_b64 s[6:7], s[88:89]
	v_mov_b32_e32 v1, v181
	s_waitcnt lgkmcnt(0)
	v_mov_b32_e32 v0, v181
	v_writelane_b32 v254, s0, 25
	s_barrier
	s_nop 0
	v_writelane_b32 v254, s1, 26
	v_writelane_b32 v254, s2, 27
	v_writelane_b32 v254, s3, 28
	v_readfirstlane_b32 s0, v167
	s_lshr_b32 s0, s0, 8
	v_readlane_b32 s2, v254, 1
	s_mul_i32 s0, s0, s2
	v_readlane_b32 s1, v254, 0
	s_add_i32 s0, s0, s1
	v_ashrrev_i32_e32 v0, 6, v0
	s_lshl_b32 s8, s0, 2
	v_add_u32_e32 v2, s8, v0
	s_movk_i32 s0, 0x4400
	v_cmp_gt_i32_e32 vcc, s0, v2
	v_mbcnt_lo_u32_b32 v71, -1, 0
	v_readlane_b32 s3, v254, 2
	s_and_saveexec_b64 s[0:1], vcc
	s_cbranch_execz .LBB0_391
	s_load_dwordx2 s[2:3], s[88:89], 0x0
	s_load_dwordx2 s[4:5], s[88:89], 0x10
	s_load_dwordx2 s[10:11], s[88:89], 0x30
	s_load_dwordx2 s[6:7], s[88:89], 0xf0
	s_load_dwordx2 s[8:9], s[88:89], 0x110
	v_readfirstlane_b32 s16, v167
	v_readlane_b32 s12, v254, 0
	v_readlane_b32 s13, v254, 1
	s_lshr_b32 s14, s16, 8
	s_mul_i32 s14, s14, s13
	s_add_u32 s14, s14, s12
	s_lshl_b32 s14, s14, 2
	s_bfe_u32 s16, s16, 0x20006
	s_add_u32 s16, s16, s14
	s_mov_b32 s17, 0x800000
	v_mov_b32_e32 v150, 0x358637bd
	v_and_b32_e32 v146, 63, v167
	v_lshlrev_b32_e32 v144, 4, v146
	v_add_u32_e32 v145, 0x1000, v144
	v_lshlrev_b32_e32 v146, 3, v146
	s_waitcnt lgkmcnt(0)
	global_load_dwordx4 v[112:115], v144, s[10:11]
	global_load_dwordx4 v[116:119], v144, s[10:11] offset:1024
	global_load_dwordx4 v[120:123], v144, s[10:11] offset:2048
	global_load_dwordx4 v[124:127], v144, s[10:11] offset:3072
	global_load_dwordx4 v[128:131], v145, s[10:11]
	global_load_dwordx4 v[132:135], v145, s[10:11] offset:1024
	global_load_dwordx4 v[136:139], v145, s[10:11] offset:2048
	global_load_dwordx4 v[140:143], v145, s[10:11] offset:3072
	s_cmp_lt_u32 s16, 0x4400
	s_cbranch_scc0 .Lpre_done
.Lpre_row:
	s_lshl_b32 s18, s16, 13
	s_add_u32 s10, s2, s18
	s_addc_u32 s11, s3, 0
	s_cmp_lt_u32 s16, 0x4000
	s_cbranch_scc1 .Lpre_lat
	s_add_u32 s18, s16, 0xffffc000
	s_lshl_b32 s18, s18, 13
	s_add_u32 s10, s4, s18
	s_addc_u32 s11, s5, 0
.Lpre_lat:
	s_lshr_b32 s18, s16, 12
	s_min_u32 s18, s18, 4
	s_mul_i32 s18, s18, 0x6000
	s_add_u32 s12, s6, s18
	s_addc_u32 s13, s7, 0
	s_add_u32 s14, s12, 0x2000
	s_addc_u32 s15, s13, 0
	global_load_dwordx4 v[0:3], v144, s[10:11]
	global_load_dwordx4 v[4:7], v144, s[10:11] offset:1024
	global_load_dwordx4 v[8:11], v144, s[10:11] offset:2048
	global_load_dwordx4 v[12:15], v144, s[10:11] offset:3072
	global_load_dwordx4 v[16:19], v145, s[10:11]
	global_load_dwordx4 v[20:23], v145, s[10:11] offset:1024
	global_load_dwordx4 v[24:27], v145, s[10:11] offset:2048
	global_load_dwordx4 v[28:31], v145, s[10:11] offset:3072
	global_load_dwordx4 v[32:35], v144, s[12:13]
	global_load_dwordx4 v[36:39], v144, s[12:13] offset:1024
	global_load_dwordx4 v[40:43], v144, s[12:13] offset:2048
	global_load_dwordx4 v[44:47], v144, s[12:13] offset:3072
	global_load_dwordx4 v[48:51], v145, s[12:13]
	global_load_dwordx4 v[52:55], v145, s[12:13] offset:1024
	global_load_dwordx4 v[56:59], v145, s[12:13] offset:2048
	global_load_dwordx4 v[60:63], v145, s[12:13] offset:3072
	global_load_dwordx4 v[72:75], v144, s[14:15]
	global_load_dwordx4 v[76:79], v144, s[14:15] offset:1024
	global_load_dwordx4 v[80:83], v144, s[14:15] offset:2048
	global_load_dwordx4 v[84:87], v144, s[14:15] offset:3072
	global_load_dwordx4 v[88:91], v145, s[14:15]
	global_load_dwordx4 v[92:95], v145, s[14:15] offset:1024
	global_load_dwordx4 v[96:99], v145, s[14:15] offset:2048
	global_load_dwordx4 v[100:103], v145, s[14:15] offset:3072
	s_lshl_b32 s18, s16, 12
	s_add_u32 s10, s8, s18
	s_addc_u32 s11, s9, 0
	s_waitcnt vmcnt(16)
	v_mul_f32_e32 v104, v1, v1
	v_fmac_f32_e32 v104, v0, v0
	v_fmac_f32_e32 v104, v2, v2
	v_fmac_f32_e32 v104, v3, v3
	v_mul_f32_e32 v105, v5, v5
	v_fmac_f32_e32 v105, v4, v4
	v_fmac_f32_e32 v105, v6, v6
	v_fmac_f32_e32 v105, v7, v7
	v_add_f32_e32 v147, v104, v105
	v_mul_f32_e32 v106, v9, v9
	v_fmac_f32_e32 v106, v8, v8
	v_fmac_f32_e32 v106, v10, v10
	v_fmac_f32_e32 v106, v11, v11
	v_add_f32_e32 v147, v147, v106
	v_mul_f32_e32 v107, v13, v13
	v_fmac_f32_e32 v107, v12, v12
	v_fmac_f32_e32 v107, v14, v14
	v_fmac_f32_e32 v107, v15, v15
	v_add_f32_e32 v147, v147, v107
	v_mul_f32_e32 v104, v17, v17
	v_fmac_f32_e32 v104, v16, v16
	v_fmac_f32_e32 v104, v18, v18
	v_fmac_f32_e32 v104, v19, v19
	v_add_f32_e32 v147, v147, v104
	v_mul_f32_e32 v105, v21, v21
	v_fmac_f32_e32 v105, v20, v20
	v_fmac_f32_e32 v105, v22, v22
	v_fmac_f32_e32 v105, v23, v23
	v_add_f32_e32 v147, v147, v105
	v_mul_f32_e32 v106, v25, v25
	v_fmac_f32_e32 v106, v24, v24
	v_fmac_f32_e32 v106, v26, v26
	v_fmac_f32_e32 v106, v27, v27
	v_add_f32_e32 v147, v147, v106
	v_mul_f32_e32 v107, v29, v29
	v_fmac_f32_e32 v107, v28, v28
	v_fmac_f32_e32 v107, v30, v30
	v_fmac_f32_e32 v107, v31, v31
	v_add_f32_e32 v147, v147, v107
	v_mov_b32_e32 v149, v147
	s_nop 1
	v_permlane32_swap_b32_e32 v147, v149
	s_nop 0
	v_add_f32_e32 v147, v147, v149
	v_mov_b32_e32 v149, v147
	s_nop 1
	v_permlane16_swap_b32_e32 v147, v149
	s_nop 0
	v_add_f32_e32 v147, v147, v149
	s_nop 1
	v_add_f32_dpp v147, v147, v147 row_ror:8 row_mask:0xf bank_mask:0xf
	s_nop 1
	v_add_f32_dpp v147, v147, v147 row_ror:4 row_mask:0xf bank_mask:0xf
	s_nop 1
	v_add_f32_dpp v147, v147, v147 row_ror:2 row_mask:0xf bank_mask:0xf
	s_nop 1
	v_add_f32_dpp v147, v147, v147 row_ror:1 row_mask:0xf bank_mask:0xf
	v_fmamk_f32 v147, v147, 0x3a000000, v150
	v_mul_f32_e32 v149, 0x4b800000, v147
	v_cmp_gt_f32_e32 vcc, s17, v147
	s_nop 1
	v_cndmask_b32_e32 v147, v147, v149, vcc
	v_rsq_f32_e32 v148, v147
	s_nop 0
	v_mul_f32_e32 v149, 0x45800000, v148
	v_cndmask_b32_e32 v148, v148, v149, vcc
	s_waitcnt vmcnt(0)
	v_mul_f32_e32 v0, v0, v148
	v_mul_f32_e32 v0, v112, v0
	v_add_f32_e32 v72, 1.0, v72
	v_fma_f32 v0, v72, v0, v32
	v_mul_f32_e32 v1, v1, v148
	v_mul_f32_e32 v1, v113, v1
	v_add_f32_e32 v73, 1.0, v73
	v_fma_f32 v1, v73, v1, v33
	v_mul_f32_e32 v2, v2, v148
	v_mul_f32_e32 v2, v114, v2
	v_add_f32_e32 v74, 1.0, v74
	v_fma_f32 v2, v74, v2, v34
	v_mul_f32_e32 v3, v3, v148
	v_mul_f32_e32 v3, v115, v3
	v_add_f32_e32 v75, 1.0, v75
	v_fma_f32 v3, v75, v3, v35
	v_cvt_pk_bf16_f32 v0, v0, v1
	v_cvt_pk_bf16_f32 v1, v2, v3
	global_store_dwordx2 v146, v[0:1], s[10:11]
	v_mul_f32_e32 v4, v4, v148
	v_mul_f32_e32 v4, v116, v4
	v_add_f32_e32 v76, 1.0, v76
	v_fma_f32 v4, v76, v4, v36
	v_mul_f32_e32 v5, v5, v148
	v_mul_f32_e32 v5, v117, v5
	v_add_f32_e32 v77, 1.0, v77
	v_fma_f32 v5, v77, v5, v37
	v_mul_f32_e32 v6, v6, v148
	v_mul_f32_e32 v6, v118, v6
	v_add_f32_e32 v78, 1.0, v78
	v_fma_f32 v6, v78, v6, v38
	v_mul_f32_e32 v7, v7, v148
	v_mul_f32_e32 v7, v119, v7
	v_add_f32_e32 v79, 1.0, v79
	v_fma_f32 v7, v79, v7, v39
	v_cvt_pk_bf16_f32 v4, v4, v5
	v_cvt_pk_bf16_f32 v5, v6, v7
	global_store_dwordx2 v146, v[4:5], s[10:11] offset:512
	v_mul_f32_e32 v8, v8, v148
	v_mul_f32_e32 v8, v120, v8
	v_add_f32_e32 v80, 1.0, v80
	v_fma_f32 v8, v80, v8, v40
	v_mul_f32_e32 v9, v9, v148
	v_mul_f32_e32 v9, v121, v9
	v_add_f32_e32 v81, 1.0, v81
	v_fma_f32 v9, v81, v9, v41
	v_mul_f32_e32 v10, v10, v148
	v_mul_f32_e32 v10, v122, v10
	v_add_f32_e32 v82, 1.0, v82
	v_fma_f32 v10, v82, v10, v42
	v_mul_f32_e32 v11, v11, v148
	v_mul_f32_e32 v11, v123, v11
	v_add_f32_e32 v83, 1.0, v83
	v_fma_f32 v11, v83, v11, v43
	v_cvt_pk_bf16_f32 v8, v8, v9
	v_cvt_pk_bf16_f32 v9, v10, v11
	global_store_dwordx2 v146, v[8:9], s[10:11] offset:1024
	v_mul_f32_e32 v12, v12, v148
	v_mul_f32_e32 v12, v124, v12
	v_add_f32_e32 v84, 1.0, v84
	v_fma_f32 v12, v84, v12, v44
	v_mul_f32_e32 v13, v13, v148
	v_mul_f32_e32 v13, v125, v13
	v_add_f32_e32 v85, 1.0, v85
	v_fma_f32 v13, v85, v13, v45
	v_mul_f32_e32 v14, v14, v148
	v_mul_f32_e32 v14, v126, v14
	v_add_f32_e32 v86, 1.0, v86
	v_fma_f32 v14, v86, v14, v46
	v_mul_f32_e32 v15, v15, v148
	v_mul_f32_e32 v15, v127, v15
	v_add_f32_e32 v87, 1.0, v87
	v_fma_f32 v15, v87, v15, v47
	v_cvt_pk_bf16_f32 v12, v12, v13
	v_cvt_pk_bf16_f32 v13, v14, v15
	global_store_dwordx2 v146, v[12:13], s[10:11] offset:1536
	v_mul_f32_e32 v16, v16, v148
	v_mul_f32_e32 v16, v128, v16
	v_add_f32_e32 v88, 1.0, v88
	v_fma_f32 v16, v88, v16, v48
	v_mul_f32_e32 v17, v17, v148
	v_mul_f32_e32 v17, v129, v17
	v_add_f32_e32 v89, 1.0, v89
	v_fma_f32 v17, v89, v17, v49
	v_mul_f32_e32 v18, v18, v148
	v_mul_f32_e32 v18, v130, v18
	v_add_f32_e32 v90, 1.0, v90
	v_fma_f32 v18, v90, v18, v50
	v_mul_f32_e32 v19, v19, v148
	v_mul_f32_e32 v19, v131, v19
	v_add_f32_e32 v91, 1.0, v91
	v_fma_f32 v19, v91, v19, v51
	v_cvt_pk_bf16_f32 v16, v16, v17
	v_cvt_pk_bf16_f32 v17, v18, v19
	global_store_dwordx2 v146, v[16:17], s[10:11] offset:2048
	v_mul_f32_e32 v20, v20, v148
	v_mul_f32_e32 v20, v132, v20
	v_add_f32_e32 v92, 1.0, v92
	v_fma_f32 v20, v92, v20, v52
	v_mul_f32_e32 v21, v21, v148
	v_mul_f32_e32 v21, v133, v21
	v_add_f32_e32 v93, 1.0, v93
	v_fma_f32 v21, v93, v21, v53
	v_mul_f32_e32 v22, v22, v148
	v_mul_f32_e32 v22, v134, v22
	v_add_f32_e32 v94, 1.0, v94
	v_fma_f32 v22, v94, v22, v54
	v_mul_f32_e32 v23, v23, v148
	v_mul_f32_e32 v23, v135, v23
	v_add_f32_e32 v95, 1.0, v95
	v_fma_f32 v23, v95, v23, v55
	v_cvt_pk_bf16_f32 v20, v20, v21
	v_cvt_pk_bf16_f32 v21, v22, v23
	global_store_dwordx2 v146, v[20:21], s[10:11] offset:2560
	v_mul_f32_e32 v24, v24, v148
	v_mul_f32_e32 v24, v136, v24
	v_add_f32_e32 v96, 1.0, v96
	v_fma_f32 v24, v96, v24, v56
	v_mul_f32_e32 v25, v25, v148
	v_mul_f32_e32 v25, v137, v25
	v_add_f32_e32 v97, 1.0, v97
	v_fma_f32 v25, v97, v25, v57
	v_mul_f32_e32 v26, v26, v148
	v_mul_f32_e32 v26, v138, v26
	v_add_f32_e32 v98, 1.0, v98
	v_fma_f32 v26, v98, v26, v58
	v_mul_f32_e32 v27, v27, v148
	v_mul_f32_e32 v27, v139, v27
	v_add_f32_e32 v99, 1.0, v99
	v_fma_f32 v27, v99, v27, v59
	v_cvt_pk_bf16_f32 v24, v24, v25
	v_cvt_pk_bf16_f32 v25, v26, v27
	global_store_dwordx2 v146, v[24:25], s[10:11] offset:3072
	v_mul_f32_e32 v28, v28, v148
	v_mul_f32_e32 v28, v140, v28
	v_add_f32_e32 v100, 1.0, v100
	v_fma_f32 v28, v100, v28, v60
	v_mul_f32_e32 v29, v29, v148
	v_mul_f32_e32 v29, v141, v29
	v_add_f32_e32 v101, 1.0, v101
	v_fma_f32 v29, v101, v29, v61
	v_mul_f32_e32 v30, v30, v148
	v_mul_f32_e32 v30, v142, v30
	v_add_f32_e32 v102, 1.0, v102
	v_fma_f32 v30, v102, v30, v62
	v_mul_f32_e32 v31, v31, v148
	v_mul_f32_e32 v31, v143, v31
	v_add_f32_e32 v103, 1.0, v103
	v_fma_f32 v31, v103, v31, v63
	v_cvt_pk_bf16_f32 v28, v28, v29
	v_cvt_pk_bf16_f32 v29, v30, v31
	global_store_dwordx2 v146, v[28:29], s[10:11] offset:3584
	s_add_u32 s16, s16, 0x800
	s_cmp_lt_u32 s16, 0x4400
	s_cbranch_scc1 .Lpre_row
.Lpre_done:
.LBB0_391:
	s_or_b64 exec, exec, s[0:1]
	s_mov_b64 s[2:3], s[88:89]
	s_getreg_b32 s4, hwreg(HW_REG_XCC_ID, 0, 4)
	s_waitcnt vmcnt(0)
	s_barrier
	s_mov_b64 s[0:1], exec
	v_readlane_b32 s6, v254, 5
	v_readlane_b32 s7, v254, 6
	s_and_b64 s[6:7], s[0:1], s[6:7]
	s_mov_b64 exec, s[6:7]
	s_cbranch_execz .LBB0_443
	s_add_i32 s5, 0, 0x220f0
	v_mov_b32_e32 v0, s5
	s_load_dwordx2 s[2:3], s[2:3], 0x170
	s_waitcnt vmcnt(0) expcnt(0) lgkmcnt(0)
	ds_read_b32 v2, v0
	s_add_i32 s5, 0, 0x220f4
	v_mov_b32_e32 v0, s5
	ds_read_b32 v0, v0
	s_and_b32 s18, s4, 15
	s_waitcnt lgkmcnt(1)
	v_cmp_ne_u32_e32 vcc, 0, v2
	s_cbranch_vccnz .LBB0_407
	v_readlane_b32 s4, v254, 1
	v_readlane_b32 s5, v254, 2
	s_mul_i32 s19, s5, s24
	s_mul_i32 s19, s19, s4
	s_add_u32 s4, s2, 0x1000
	s_addc_u32 s5, s3, 0
	s_add_u32 s6, s2, 0x1100
	s_addc_u32 s7, s3, 0
	s_add_u32 s8, s2, 0x1200
	s_addc_u32 s9, s3, 0
	s_add_u32 s10, s2, 0x1300
	s_addc_u32 s11, s3, 0
	s_mov_b32 s20, 1
	v_mov_b32_e32 v16, 0
	s_branch .LBB0_395

.LBB0_1088:
	s_cmpk_gt_i32 s16, 0x1ff
	s_mov_b64 s[0:1], -1
	s_cbranch_scc0 .LBB0_1090
	v_mov_b32_e32 v0, v181
	s_lshl_b32 s0, s16, 2
	s_addk_i32 s0, 0x3800
	v_ashrrev_i32_e32 v0, 6, v0
	v_add_u32_e32 v0, s0, v0
	v_mov_b32_e32 v4, v181
	v_ashrrev_i32_e32 v1, 31, v0
	v_lshlrev_b64 v[2:3], 12, v[0:1]
	v_lshlrev_b32_e32 v1, 4, v4
	s_waitcnt lgkmcnt(0)
	v_lshl_add_u64 v[2:3], s[12:13], 0, v[2:3]
	v_and_b32_e32 v164, 0x3f0, v1
	v_lshl_add_u64 v[8:9], v[2:3], 0, v[164:165]
	global_load_dwordx4 v[12:15], v[8:9], off
	global_load_dwordx4 v[16:19], v[8:9], off offset:2048
	global_load_dwordx4 v[42:45], v[8:9], off offset:1024
	v_xor_b32_e32 v1, 32, v192
	s_waitcnt vmcnt(2)
	v_and_b32_e32 v5, 0xffff0000, v12
	s_waitcnt vmcnt(1)
	v_and_b32_e32 v4, 0xffff0000, v16
	s_waitcnt vmcnt(0)
	v_lshlrev_b32_e32 v25, 16, v44
	v_and_b32_e32 v24, 0xffff0000, v44
	v_lshlrev_b32_e32 v23, 16, v45
	v_and_b32_e32 v22, 0xffff0000, v45
	global_load_dwordx4 v[44:47], v[8:9], off offset:3072
	v_lshlrev_b32_e32 v39, 16, v12
	v_lshlrev_b32_e32 v38, 16, v16
	v_pk_mul_f32 v[2:3], v[4:5], v[4:5]
	v_lshlrev_b32_e32 v37, 16, v13
	v_pk_fma_f32 v[20:21], v[38:39], v[38:39], v[2:3]
	v_lshlrev_b32_e32 v36, 16, v17
	v_and_b32_e32 v33, 0xffff0000, v13
	v_and_b32_e32 v32, 0xffff0000, v17
	v_lshlrev_b32_e32 v35, 16, v14
	v_and_b32_e32 v7, 0xffff0000, v14
	v_lshlrev_b32_e32 v29, 16, v15
	v_and_b32_e32 v27, 0xffff0000, v15
	v_pk_fma_f32 v[14:15], v[36:37], v[36:37], v[20:21]
	v_lshlrev_b32_e32 v34, 16, v18
	v_pk_fma_f32 v[14:15], v[32:33], v[32:33], v[14:15]
	v_and_b32_e32 v6, 0xffff0000, v18
	v_pk_fma_f32 v[14:15], v[34:35], v[34:35], v[14:15]
	v_lshlrev_b32_e32 v28, 16, v19
	v_pk_fma_f32 v[14:15], v[6:7], v[6:7], v[14:15]
	v_and_b32_e32 v26, 0xffff0000, v19
	v_pk_fma_f32 v[14:15], v[28:29], v[28:29], v[14:15]
	v_lshlrev_b32_e32 v21, 16, v42
	v_pk_fma_f32 v[30:31], v[26:27], v[26:27], v[14:15]
	v_and_b32_e32 v19, 0xffff0000, v42
	v_lshlrev_b32_e32 v17, 16, v43
	v_pk_mul_f32 v[2:3], v[24:25], v[24:25]
	v_and_b32_e32 v15, 0xffff0000, v43
	v_mov_b32_e32 v43, v3
	s_waitcnt vmcnt(0)
	v_lshlrev_b32_e32 v20, 16, v44
	v_and_b32_e32 v18, 0xffff0000, v44
	v_pk_fma_f32 v[30:31], v[20:21], v[20:21], v[30:31]
	v_lshlrev_b32_e32 v13, 16, v46
	v_and_b32_e32 v12, 0xffff0000, v46
	v_lshlrev_b32_e32 v16, 16, v45
	v_pk_fma_f32 v[30:31], v[18:19], v[18:19], v[30:31]
	v_pk_mul_f32 v[40:41], v[12:13], v[12:13]
	v_and_b32_e32 v14, 0xffff0000, v45
	v_pk_fma_f32 v[30:31], v[16:17], v[16:17], v[30:31]
	v_mov_b32_e32 v42, v41
	v_pk_fma_f32 v[30:31], v[14:15], v[14:15], v[30:31]
	v_lshlrev_b32_e32 v11, 16, v47
	v_pk_add_f32 v[42:43], v[42:43], v[30:31]
	v_mov_b64_e32 v[30:31], s[14:15]
	v_mad_i64_i32 v[30:31], s[0:1], v0, s49, v[30:31]
	v_and_b32_e32 v0, 64, v192
	v_add_u32_e32 v0, 64, v0
	v_cmp_lt_i32_e32 vcc, v1, v0
	v_and_b32_e32 v10, 0xffff0000, v47
	v_pk_mul_f32 v[44:45], v[22:23], v[22:23]
	v_cndmask_b32_e32 v1, v192, v1, vcc
	v_lshlrev_b32_e32 v48, 2, v1
	v_xor_b32_e32 v1, 16, v192
	v_cmp_lt_i32_e32 vcc, v1, v0
	v_pk_mul_f32 v[46:47], v[10:11], v[10:11]
	v_mov_b32_e32 v41, v2
	v_cndmask_b32_e32 v1, v192, v1, vcc
	v_lshlrev_b32_e32 v49, 2, v1
	v_xor_b32_e32 v1, 8, v192
	v_cmp_lt_i32_e32 vcc, v1, v0
	v_mov_b32_e32 v2, v47
	v_mov_b32_e32 v3, v45
	v_cndmask_b32_e32 v1, v192, v1, vcc
	v_lshlrev_b32_e32 v50, 2, v1
	v_xor_b32_e32 v1, 4, v192
	v_cmp_lt_i32_e32 vcc, v1, v0
	v_mov_b32_e32 v47, v44
	s_mov_b32 s0, 0x3a800000
	v_cndmask_b32_e32 v1, v192, v1, vcc
	v_lshlrev_b32_e32 v51, 2, v1
	v_xor_b32_e32 v1, 2, v192
	v_cmp_lt_i32_e32 vcc, v1, v0
	s_nop 1
	v_cndmask_b32_e32 v1, v192, v1, vcc
	v_lshlrev_b32_e32 v52, 2, v1
	v_xor_b32_e32 v1, 1, v192
	v_cmp_lt_i32_e32 vcc, v1, v0
	s_nop 1
	v_cndmask_b32_e32 v0, v192, v1, vcc
	v_lshlrev_b32_e32 v53, 2, v0
	v_pk_add_f32 v[0:1], v[40:41], v[42:43]
	v_lshl_add_u64 v[40:41], v[30:31], 0, v[164:165]
	v_pk_add_f32 v[0:1], v[2:3], v[0:1]
	v_or_b32_e32 v164, 0x400, v164
	v_pk_add_f32 v[0:1], v[46:47], v[0:1]
	v_mov_b32_e32 v2, v0
	v_mov_b32_e32 v3, v1
	s_nop 1
	v_permlane32_swap_b32_e32 v0, v2
	v_permlane32_swap_b32_e32 v1, v3
	s_nop 0
	v_add_f32_e32 v0, v0, v2
	v_add_f32_e32 v1, v1, v3
	v_mov_b32_e32 v2, v0
	v_mov_b32_e32 v3, v1
	s_nop 1
	v_permlane16_swap_b32_e32 v0, v2
	v_permlane16_swap_b32_e32 v1, v3
	s_nop 0
	v_add_f32_e32 v0, v0, v2
	v_add_f32_e32 v1, v1, v3
	s_nop 1
	v_add_f32_dpp v0, v0, v0 row_ror:8 row_mask:0xf bank_mask:0xf
	v_add_f32_dpp v1, v1, v1 row_ror:8 row_mask:0xf bank_mask:0xf
	s_nop 1
	v_add_f32_dpp v0, v0, v0 row_ror:4 row_mask:0xf bank_mask:0xf
	v_add_f32_dpp v1, v1, v1 row_ror:4 row_mask:0xf bank_mask:0xf
	s_nop 1
	v_add_f32_dpp v0, v0, v0 row_ror:2 row_mask:0xf bank_mask:0xf
	v_add_f32_dpp v1, v1, v1 row_ror:2 row_mask:0xf bank_mask:0xf
	s_nop 1
	v_add_f32_dpp v0, v0, v0 row_ror:1 row_mask:0xf bank_mask:0xf
	v_add_f32_dpp v1, v1, v1 row_ror:1 row_mask:0xf bank_mask:0xf
	s_nop 1
	s_nop 0
	v_pk_fma_f32 v[0:1], v[0:1], s[0:1], v[166:167] op_sel_hi:[1,0,0]
	s_nop 0
	v_mul_f32_e32 v2, 0x4b800000, v1
	v_cmp_gt_f32_e64 s[10:11], s58, v1
	v_cmp_gt_f32_e32 vcc, s58, v0
	s_nop 0
	v_cndmask_b32_e64 v1, v1, v2, s[10:11]
	v_rsq_f32_e32 v1, v1
	s_nop 0
	v_mul_f32_e32 v2, 0x45800000, v1
	v_cndmask_b32_e64 v43, v1, v2, s[10:11]
	v_mul_f32_e32 v1, 0x4b800000, v0
	v_cndmask_b32_e32 v0, v0, v1, vcc
	v_rsq_f32_e32 v0, v0
	v_mul_f32_e32 v15, v43, v15
	v_mul_f32_e32 v1, 0x45800000, v0
	v_cndmask_b32_e32 v42, v0, v1, vcc
	global_load_dwordx4 v[0:3], v[40:41], off offset:1664
	v_mul_f32_e32 v4, v42, v4
	v_mul_f32_e32 v6, v42, v6
	v_mul_f32_e32 v26, v42, v26
	v_mul_f32_e32 v14, v42, v14
	v_mul_f32_e32 v13, v42, v13
	v_mul_f32_e32 v12, v42, v12
	v_mul_f32_e32 v11, v42, v11
	v_mul_f32_e32 v10, v42, v10
	s_waitcnt vmcnt(0)
	v_lshlrev_b32_e32 v59, 16, v0
	v_and_b32_e32 v58, 0xffff0000, v0
	v_lshlrev_b32_e32 v55, 16, v1
	v_and_b32_e32 v53, 0xffff0000, v1
	v_lshlrev_b32_e32 v51, 16, v2
	v_and_b32_e32 v49, 0xffff0000, v2
	v_lshlrev_b32_e32 v47, 16, v3
	v_and_b32_e32 v45, 0xffff0000, v3
	global_load_dwordx4 v[0:3], v[40:41], off offset:3712
	s_waitcnt vmcnt(0)
	v_lshlrev_b32_e32 v54, 16, v1
	v_and_b32_e32 v52, 0xffff0000, v1
	v_mul_f32_e32 v1, 0xbfb8aa3b, v59
	v_exp_f32_e32 v1, v1
	v_lshlrev_b32_e32 v50, 16, v2
	v_and_b32_e32 v48, 0xffff0000, v2
	v_lshlrev_b32_e32 v46, 16, v3
	v_add_f32_e32 v1, 1.0, v1
	v_div_scale_f32 v2, s[0:1], v1, v1, v59
	v_and_b32_e32 v44, 0xffff0000, v3
	v_rcp_f32_e32 v3, v2
	v_lshlrev_b32_e32 v57, 16, v0
	v_and_b32_e32 v56, 0xffff0000, v0
	v_mul_f32_e32 v0, v43, v39
	v_fma_f32 v39, -v2, v3, 1.0
	v_fmac_f32_e32 v3, v39, v3
	v_div_scale_f32 v39, vcc, v59, v1, v59
	v_mul_f32_e32 v60, v39, v3
	v_fma_f32 v61, -v2, v60, v39
	v_fmac_f32_e32 v60, v61, v3
	v_fma_f32 v2, -v2, v60, v39
	v_div_fmas_f32 v2, v2, v3, v60
	v_div_fixup_f32 v1, v2, v1, v59
	v_mul_f32_e32 v2, 0xbfb8aa3b, v58
	v_exp_f32_e32 v2, v2
	v_mul_f32_e32 v0, v0, v1
	v_mul_f32_e32 v1, v43, v5
	v_add_f32_e32 v2, 1.0, v2
	v_div_scale_f32 v3, s[0:1], v2, v2, v58
	v_rcp_f32_e32 v5, v3
	s_nop 0
	v_fma_f32 v39, -v3, v5, 1.0
	v_fmac_f32_e32 v5, v39, v5
	v_div_scale_f32 v39, vcc, v58, v2, v58
	v_mul_f32_e32 v59, v39, v5
	v_fma_f32 v60, -v3, v59, v39
	v_fmac_f32_e32 v59, v60, v5
	v_fma_f32 v3, -v3, v59, v39
	v_div_fmas_f32 v3, v3, v5, v59
	v_div_fixup_f32 v2, v3, v2, v58
	v_mul_f32_e32 v1, v1, v2
	v_mul_f32_e32 v2, 0xbfb8aa3b, v55
	v_exp_f32_e32 v2, v2
	v_cvt_pk_bf16_f32 v0, v0, v1
	v_mul_f32_e32 v1, v43, v37
	v_add_f32_e32 v2, 1.0, v2
	v_div_scale_f32 v3, s[0:1], v2, v2, v55
	v_rcp_f32_e32 v5, v3
	s_nop 0
	v_fma_f32 v37, -v3, v5, 1.0
	v_fmac_f32_e32 v5, v37, v5
	v_div_scale_f32 v37, vcc, v55, v2, v55
	v_mul_f32_e32 v39, v37, v5
	v_fma_f32 v58, -v3, v39, v37
	v_fmac_f32_e32 v39, v58, v5
	v_fma_f32 v3, -v3, v39, v37
	v_div_fmas_f32 v3, v3, v5, v39
	v_div_fixup_f32 v2, v3, v2, v55
	v_mul_f32_e32 v3, 0xbfb8aa3b, v53
	v_exp_f32_e32 v3, v3
	v_mul_f32_e32 v1, v1, v2
	v_mul_f32_e32 v2, v43, v33
	v_add_f32_e32 v3, 1.0, v3
	v_div_scale_f32 v5, s[0:1], v3, v3, v53
	v_rcp_f32_e32 v33, v5
	s_nop 0
	v_fma_f32 v37, -v5, v33, 1.0
	v_fmac_f32_e32 v33, v37, v33
	v_div_scale_f32 v37, vcc, v53, v3, v53
	v_mul_f32_e32 v39, v37, v33
	v_fma_f32 v55, -v5, v39, v37
	v_fmac_f32_e32 v39, v55, v33
	v_fma_f32 v5, -v5, v39, v37
	v_div_fmas_f32 v5, v5, v33, v39
	v_div_fixup_f32 v3, v5, v3, v53
	v_mul_f32_e32 v2, v2, v3
	v_mul_f32_e32 v3, 0xbfb8aa3b, v51
	v_exp_f32_e32 v3, v3
	v_cvt_pk_bf16_f32 v1, v1, v2
	v_mul_f32_e32 v2, v43, v35
	v_add_f32_e32 v3, 1.0, v3
	v_div_scale_f32 v5, s[0:1], v3, v3, v51
	v_rcp_f32_e32 v33, v5
	s_nop 0
	v_fma_f32 v35, -v5, v33, 1.0
	v_fmac_f32_e32 v33, v35, v33
	v_div_scale_f32 v35, vcc, v51, v3, v51
	v_mul_f32_e32 v37, v35, v33
	v_fma_f32 v39, -v5, v37, v35
	v_fmac_f32_e32 v37, v39, v33
	v_fma_f32 v5, -v5, v37, v35
	v_div_fmas_f32 v5, v5, v33, v37
	v_div_fixup_f32 v3, v5, v3, v51
	v_mul_f32_e32 v5, 0xbfb8aa3b, v49
	v_exp_f32_e32 v5, v5
	v_mul_f32_e32 v2, v2, v3
	v_mul_f32_e32 v3, v43, v7
	v_add_f32_e32 v5, 1.0, v5
	v_div_scale_f32 v7, s[0:1], v5, v5, v49
	v_rcp_f32_e32 v33, v7
	s_nop 0
	v_fma_f32 v35, -v7, v33, 1.0
	v_fmac_f32_e32 v33, v35, v33
	v_div_scale_f32 v35, vcc, v49, v5, v49
	v_mul_f32_e32 v37, v35, v33
	v_fma_f32 v39, -v7, v37, v35
	v_fmac_f32_e32 v37, v39, v33
	v_fma_f32 v7, -v7, v37, v35
	v_div_fmas_f32 v7, v7, v33, v37
	v_div_fixup_f32 v5, v7, v5, v49
	v_mul_f32_e32 v3, v3, v5
	v_mul_f32_e32 v5, 0xbfb8aa3b, v47
	v_exp_f32_e32 v5, v5
	v_cvt_pk_bf16_f32 v2, v2, v3
	v_mul_f32_e32 v3, v43, v29
	v_add_f32_e32 v5, 1.0, v5
	v_div_scale_f32 v7, s[0:1], v5, v5, v47
	v_rcp_f32_e32 v29, v7
	s_nop 0
	v_fma_f32 v33, -v7, v29, 1.0
	v_fmac_f32_e32 v29, v33, v29
	v_div_scale_f32 v33, vcc, v47, v5, v47
	v_mul_f32_e32 v35, v33, v29
	v_fma_f32 v37, -v7, v35, v33
	v_fmac_f32_e32 v35, v37, v29
	v_fma_f32 v7, -v7, v35, v33
	v_div_fmas_f32 v7, v7, v29, v35
	v_div_fixup_f32 v5, v7, v5, v47
	v_mul_f32_e32 v7, 0xbfb8aa3b, v45
	v_exp_f32_e32 v7, v7
	v_mul_f32_e32 v3, v3, v5
	v_mul_f32_e32 v5, v43, v27
	v_add_f32_e32 v7, 1.0, v7
	v_div_scale_f32 v27, s[0:1], v7, v7, v45
	v_rcp_f32_e32 v29, v27
	s_nop 0
	v_fma_f32 v33, -v27, v29, 1.0
	v_fmac_f32_e32 v29, v33, v29
	v_div_scale_f32 v33, vcc, v45, v7, v45
	v_mul_f32_e32 v35, v33, v29
	v_fma_f32 v37, -v27, v35, v33
	v_fmac_f32_e32 v35, v37, v29
	v_fma_f32 v27, -v27, v35, v33
	v_div_fmas_f32 v27, v27, v29, v35
	v_div_fixup_f32 v7, v27, v7, v45
	v_mul_f32_e32 v5, v5, v7
	v_mul_f32_e32 v7, 0xbfb8aa3b, v57
	v_exp_f32_e32 v7, v7
	v_cvt_pk_bf16_f32 v3, v3, v5
	v_mul_f32_e32 v5, v42, v38
	v_add_f32_e32 v7, 1.0, v7
	v_div_scale_f32 v27, s[0:1], v7, v7, v57
	v_rcp_f32_e32 v29, v27
	s_nop 0
	v_fma_f32 v33, -v27, v29, 1.0
	v_fmac_f32_e32 v29, v33, v29
	v_div_scale_f32 v33, vcc, v57, v7, v57
	v_mul_f32_e32 v35, v33, v29
	v_fma_f32 v37, -v27, v35, v33
	v_fmac_f32_e32 v35, v37, v29
	v_fma_f32 v27, -v27, v35, v33
	v_div_fmas_f32 v27, v27, v29, v35
	v_div_fixup_f32 v7, v27, v7, v57
	v_mul_f32_e32 v5, v5, v7
	v_mul_f32_e32 v7, 0xbfb8aa3b, v56
	v_exp_f32_e32 v7, v7
	s_nop 0
	v_add_f32_e32 v7, 1.0, v7
	v_div_scale_f32 v27, s[0:1], v7, v7, v56
	v_rcp_f32_e32 v29, v27
	s_nop 0
	v_fma_f32 v33, -v27, v29, 1.0
	v_fmac_f32_e32 v29, v33, v29
	v_div_scale_f32 v33, vcc, v56, v7, v56
	v_mul_f32_e32 v35, v33, v29
	v_fma_f32 v37, -v27, v35, v33
	v_fmac_f32_e32 v35, v37, v29
	v_fma_f32 v27, -v27, v35, v33
	v_div_fmas_f32 v27, v27, v29, v35
	v_div_fixup_f32 v7, v27, v7, v56
	v_mul_f32_e32 v4, v4, v7
	v_mul_f32_e32 v7, 0xbfb8aa3b, v54
	v_exp_f32_e32 v7, v7
	v_cvt_pk_bf16_f32 v4, v5, v4
	v_mul_f32_e32 v5, v42, v36
	v_add_f32_e32 v7, 1.0, v7
	v_div_scale_f32 v27, s[0:1], v7, v7, v54
	v_rcp_f32_e32 v29, v27
	s_nop 0
	v_fma_f32 v33, -v27, v29, 1.0
	v_fmac_f32_e32 v29, v33, v29
	v_div_scale_f32 v33, vcc, v54, v7, v54
	v_mul_f32_e32 v35, v33, v29
	v_fma_f32 v36, -v27, v35, v33
	v_fmac_f32_e32 v35, v36, v29
	v_fma_f32 v27, -v27, v35, v33
	v_div_fmas_f32 v27, v27, v29, v35
	v_div_fixup_f32 v7, v27, v7, v54
	v_mul_f32_e32 v27, 0xbfb8aa3b, v52
	v_exp_f32_e32 v27, v27
	v_mul_f32_e32 v5, v5, v7
	v_mul_f32_e32 v7, v42, v32
	v_add_f32_e32 v27, 1.0, v27
	v_div_scale_f32 v29, s[0:1], v27, v27, v52
	v_rcp_f32_e32 v32, v29
	s_nop 0
	v_fma_f32 v33, -v29, v32, 1.0
	v_fmac_f32_e32 v32, v33, v32
	v_div_scale_f32 v33, vcc, v52, v27, v52
	v_mul_f32_e32 v35, v33, v32
	v_fma_f32 v36, -v29, v35, v33
	v_fmac_f32_e32 v35, v36, v32
	v_fma_f32 v29, -v29, v35, v33
	v_div_fmas_f32 v29, v29, v32, v35
	v_div_fixup_f32 v27, v29, v27, v52
	v_mul_f32_e32 v7, v7, v27
	v_mul_f32_e32 v27, 0xbfb8aa3b, v50
	v_exp_f32_e32 v27, v27
	v_cvt_pk_bf16_f32 v5, v5, v7
	v_mul_f32_e32 v7, v42, v34
	v_add_f32_e32 v27, 1.0, v27
	v_div_scale_f32 v29, s[0:1], v27, v27, v50
	v_rcp_f32_e32 v32, v29
	s_nop 0
	v_fma_f32 v33, -v29, v32, 1.0
	v_fmac_f32_e32 v32, v33, v32
	v_div_scale_f32 v33, vcc, v50, v27, v50
	v_mul_f32_e32 v34, v33, v32
	v_fma_f32 v35, -v29, v34, v33
	v_fmac_f32_e32 v34, v35, v32
	v_fma_f32 v29, -v29, v34, v33
	v_div_fmas_f32 v29, v29, v32, v34
	v_div_fixup_f32 v27, v29, v27, v50
	v_mul_f32_e32 v7, v7, v27
	v_mul_f32_e32 v27, 0xbfb8aa3b, v48
	v_exp_f32_e32 v27, v27
	s_nop 0
	v_add_f32_e32 v27, 1.0, v27
	v_div_scale_f32 v29, s[0:1], v27, v27, v48
	v_rcp_f32_e32 v32, v29
	s_nop 0
	v_fma_f32 v33, -v29, v32, 1.0
	v_fmac_f32_e32 v32, v33, v32
	v_div_scale_f32 v33, vcc, v48, v27, v48
	v_mul_f32_e32 v34, v33, v32
	v_fma_f32 v35, -v29, v34, v33
	v_fmac_f32_e32 v34, v35, v32
	v_fma_f32 v29, -v29, v34, v33
	v_div_fmas_f32 v29, v29, v32, v34
	v_div_fixup_f32 v27, v29, v27, v48
	v_mul_f32_e32 v6, v6, v27
	v_mul_f32_e32 v27, 0xbfb8aa3b, v46
	v_exp_f32_e32 v27, v27
	v_cvt_pk_bf16_f32 v6, v7, v6
	v_mul_f32_e32 v7, v42, v28
	v_add_f32_e32 v27, 1.0, v27
	v_div_scale_f32 v28, s[0:1], v27, v27, v46
	v_rcp_f32_e32 v29, v28
	s_nop 0
	v_fma_f32 v32, -v28, v29, 1.0
	v_fmac_f32_e32 v29, v32, v29
	v_div_scale_f32 v32, vcc, v46, v27, v46
	v_mul_f32_e32 v33, v32, v29
	v_fma_f32 v34, -v28, v33, v32
	v_fmac_f32_e32 v33, v34, v29
	v_fma_f32 v28, -v28, v33, v32
	v_div_fmas_f32 v28, v28, v29, v33
	v_div_fixup_f32 v27, v28, v27, v46
	v_mul_f32_e32 v7, v7, v27
	v_mul_f32_e32 v27, 0xbfb8aa3b, v44
	v_exp_f32_e32 v27, v27
	s_nop 0
	v_add_f32_e32 v27, 1.0, v27
	v_div_scale_f32 v28, s[0:1], v27, v27, v44
	v_rcp_f32_e32 v29, v28
	s_nop 0
	v_fma_f32 v32, -v28, v29, 1.0
	v_fmac_f32_e32 v29, v32, v29
	v_div_scale_f32 v32, vcc, v44, v27, v44
	v_mul_f32_e32 v33, v32, v29
	v_fma_f32 v34, -v28, v33, v32
	v_fmac_f32_e32 v33, v34, v29
	v_fma_f32 v28, -v28, v33, v32
	v_div_fmas_f32 v28, v28, v29, v33
	v_div_fixup_f32 v27, v28, v27, v44
	v_mul_f32_e32 v26, v26, v27
	v_cvt_pk_bf16_f32 v7, v7, v26
	global_store_dwordx4 v[8:9], v[0:3], off
	global_store_dwordx4 v[8:9], v[4:7], off offset:2048
	global_load_dwordx4 v[0:3], v[40:41], off offset:2688
	s_waitcnt vmcnt(0)
	v_lshlrev_b32_e32 v33, 16, v0
	v_and_b32_e32 v34, 0xffff0000, v0
	v_lshlrev_b32_e32 v35, 16, v1
	v_and_b32_e32 v36, 0xffff0000, v1
	v_lshl_add_u64 v[0:1], v[30:31], 0, v[164:165]
	global_load_dwordx4 v[4:7], v[0:1], off offset:3712
	v_mul_f32_e32 v1, 0xbfb8aa3b, v33
	v_exp_f32_e32 v1, v1
	v_mul_f32_e32 v0, v43, v21
	v_lshlrev_b32_e32 v37, 16, v2
	v_and_b32_e32 v2, 0xffff0000, v2
	v_add_f32_e32 v1, 1.0, v1
	v_div_scale_f32 v21, s[0:1], v1, v1, v33
	v_rcp_f32_e32 v30, v21
	v_lshlrev_b32_e32 v32, 16, v3
	v_and_b32_e32 v3, 0xffff0000, v3
	v_fma_f32 v31, -v21, v30, 1.0
	v_fmac_f32_e32 v30, v31, v30
	v_div_scale_f32 v31, vcc, v33, v1, v33
	v_mul_f32_e32 v38, v31, v30
	v_fma_f32 v39, -v21, v38, v31
	v_fmac_f32_e32 v38, v39, v30
	v_fma_f32 v21, -v21, v38, v31
	v_div_fmas_f32 v21, v21, v30, v38
	v_div_fixup_f32 v1, v21, v1, v33
	v_mul_f32_e32 v0, v0, v1
	v_mul_f32_e32 v1, v43, v19
	v_mul_f32_e32 v19, 0xbfb8aa3b, v34
	v_exp_f32_e32 v19, v19
	s_waitcnt vmcnt(0)
	v_lshlrev_b32_e32 v29, 16, v4
	v_add_f32_e32 v19, 1.0, v19
	v_div_scale_f32 v21, s[0:1], v19, v19, v34
	v_rcp_f32_e32 v30, v21
	v_and_b32_e32 v4, 0xffff0000, v4
	v_lshlrev_b32_e32 v28, 16, v5
	v_and_b32_e32 v5, 0xffff0000, v5
	v_fma_f32 v31, -v21, v30, 1.0
	v_fmac_f32_e32 v30, v31, v30
	v_div_scale_f32 v31, vcc, v34, v19, v34
	v_mul_f32_e32 v33, v31, v30
	v_fma_f32 v38, -v21, v33, v31
	v_fmac_f32_e32 v33, v38, v30
	v_fma_f32 v21, -v21, v33, v31
	v_div_fmas_f32 v21, v21, v30, v33
	v_div_fixup_f32 v19, v21, v19, v34
	v_mul_f32_e32 v1, v1, v19
	v_cvt_pk_bf16_f32 v0, v0, v1
	v_mul_f32_e32 v1, v43, v17
	v_mul_f32_e32 v17, 0xbfb8aa3b, v35
	v_exp_f32_e32 v17, v17
	v_lshlrev_b32_e32 v27, 16, v6
	v_and_b32_e32 v6, 0xffff0000, v6
	v_lshlrev_b32_e32 v26, 16, v7
	v_add_f32_e32 v17, 1.0, v17
	v_div_scale_f32 v19, s[0:1], v17, v17, v35
	v_rcp_f32_e32 v21, v19
	v_and_b32_e32 v7, 0xffff0000, v7
	v_fma_f32 v30, -v19, v21, 1.0
	v_fmac_f32_e32 v21, v30, v21
	v_div_scale_f32 v30, vcc, v35, v17, v35
	v_mul_f32_e32 v31, v30, v21
	v_fma_f32 v33, -v19, v31, v30
	v_fmac_f32_e32 v31, v33, v21
	v_fma_f32 v19, -v19, v31, v30
	v_div_fmas_f32 v19, v19, v21, v31
	v_div_fixup_f32 v17, v19, v17, v35
	v_mul_f32_e32 v1, v1, v17
	v_mul_f32_e32 v17, 0xbfb8aa3b, v36
	v_exp_f32_e32 v17, v17
	s_nop 0
	v_add_f32_e32 v17, 1.0, v17
	v_div_scale_f32 v19, s[0:1], v17, v17, v36
	v_rcp_f32_e32 v21, v19
	s_nop 0
	v_fma_f32 v30, -v19, v21, 1.0
	v_fmac_f32_e32 v21, v30, v21
	v_div_scale_f32 v30, vcc, v36, v17, v36
	v_mul_f32_e32 v31, v30, v21
	v_fma_f32 v33, -v19, v31, v30
	v_fmac_f32_e32 v31, v33, v21
	v_fma_f32 v19, -v19, v31, v30
	v_div_fmas_f32 v19, v19, v21, v31
	v_div_fixup_f32 v17, v19, v17, v36
	v_mul_f32_e32 v15, v15, v17
	v_mul_f32_e32 v17, 0xbfb8aa3b, v37
	v_exp_f32_e32 v17, v17
	v_cvt_pk_bf16_f32 v1, v1, v15
	v_mul_f32_e32 v15, v43, v25
	v_add_f32_e32 v17, 1.0, v17
	v_div_scale_f32 v19, s[0:1], v17, v17, v37
	v_rcp_f32_e32 v21, v19
	s_nop 0
	v_fma_f32 v25, -v19, v21, 1.0
	v_fmac_f32_e32 v21, v25, v21
	v_div_scale_f32 v25, vcc, v37, v17, v37
	v_mul_f32_e32 v30, v25, v21
	v_fma_f32 v31, -v19, v30, v25
	v_fmac_f32_e32 v30, v31, v21
	v_fma_f32 v19, -v19, v30, v25
	v_div_fmas_f32 v19, v19, v21, v30
	v_div_fixup_f32 v17, v19, v17, v37
	v_mul_f32_e32 v19, 0xbfb8aa3b, v2
	v_exp_f32_e32 v19, v19
	v_mul_f32_e32 v15, v15, v17
	v_mul_f32_e32 v17, v43, v24
	v_add_f32_e32 v19, 1.0, v19
	v_div_scale_f32 v21, s[0:1], v19, v19, v2
	v_rcp_f32_e32 v24, v21
	s_nop 0
	v_fma_f32 v25, -v21, v24, 1.0
	v_fmac_f32_e32 v24, v25, v24
	v_div_scale_f32 v25, vcc, v2, v19, v2
	v_mul_f32_e32 v30, v25, v24
	v_fma_f32 v31, -v21, v30, v25
	v_fmac_f32_e32 v30, v31, v24
	v_fma_f32 v21, -v21, v30, v25
	v_div_fmas_f32 v21, v21, v24, v30
	v_div_fixup_f32 v2, v21, v19, v2
	v_mul_f32_e32 v2, v17, v2
	v_mul_f32_e32 v17, 0xbfb8aa3b, v32
	v_exp_f32_e32 v17, v17
	v_cvt_pk_bf16_f32 v2, v15, v2
	v_mul_f32_e32 v15, v43, v23
	v_add_f32_e32 v17, 1.0, v17
	v_div_scale_f32 v19, s[0:1], v17, v17, v32
	v_rcp_f32_e32 v21, v19
	s_nop 0
	v_fma_f32 v23, -v19, v21, 1.0
	v_fmac_f32_e32 v21, v23, v21
	v_div_scale_f32 v23, vcc, v32, v17, v32
	v_mul_f32_e32 v24, v23, v21
	v_fma_f32 v25, -v19, v24, v23
	v_fmac_f32_e32 v24, v25, v21
	v_fma_f32 v19, -v19, v24, v23
	v_div_fmas_f32 v19, v19, v21, v24
	v_div_fixup_f32 v17, v19, v17, v32
	v_mul_f32_e32 v19, 0xbfb8aa3b, v3
	v_exp_f32_e32 v19, v19
	v_mul_f32_e32 v15, v15, v17
	v_mul_f32_e32 v17, v43, v22
	v_add_f32_e32 v19, 1.0, v19
	v_div_scale_f32 v21, s[0:1], v19, v19, v3
	v_rcp_f32_e32 v22, v21
	s_nop 0
	v_fma_f32 v23, -v21, v22, 1.0
	v_fmac_f32_e32 v22, v23, v22
	v_div_scale_f32 v23, vcc, v3, v19, v3
	v_mul_f32_e32 v24, v23, v22
	v_fma_f32 v25, -v21, v24, v23
	v_fmac_f32_e32 v24, v25, v22
	v_fma_f32 v21, -v21, v24, v23
	v_div_fmas_f32 v21, v21, v22, v24
	v_div_fixup_f32 v3, v21, v19, v3
	v_mul_f32_e32 v3, v17, v3
	v_mul_f32_e32 v17, 0xbfb8aa3b, v29
	v_exp_f32_e32 v17, v17
	v_cvt_pk_bf16_f32 v3, v15, v3
	v_mul_f32_e32 v15, v42, v20
	v_add_f32_e32 v17, 1.0, v17
	v_div_scale_f32 v19, s[0:1], v17, v17, v29
	v_rcp_f32_e32 v20, v19
	s_nop 0
	v_fma_f32 v21, -v19, v20, 1.0
	v_fmac_f32_e32 v20, v21, v20
	v_div_scale_f32 v21, vcc, v29, v17, v29
	v_mul_f32_e32 v22, v21, v20
	v_fma_f32 v23, -v19, v22, v21
	v_fmac_f32_e32 v22, v23, v20
	v_fma_f32 v19, -v19, v22, v21
	v_div_fmas_f32 v19, v19, v20, v22
	v_div_fixup_f32 v17, v19, v17, v29
	v_mul_f32_e32 v15, v15, v17
	v_mul_f32_e32 v17, v42, v18
	v_mul_f32_e32 v18, 0xbfb8aa3b, v4
	v_exp_f32_e32 v18, v18
	s_nop 0
	v_add_f32_e32 v18, 1.0, v18
	v_div_scale_f32 v19, s[0:1], v18, v18, v4
	v_rcp_f32_e32 v20, v19
	s_nop 0
	v_fma_f32 v21, -v19, v20, 1.0
	v_fmac_f32_e32 v20, v21, v20
	v_div_scale_f32 v21, vcc, v4, v18, v4
	v_mul_f32_e32 v22, v21, v20
	v_fma_f32 v23, -v19, v22, v21
	v_fmac_f32_e32 v22, v23, v20
	v_fma_f32 v19, -v19, v22, v21
	v_div_fmas_f32 v19, v19, v20, v22
	v_div_fixup_f32 v4, v19, v18, v4
	v_mul_f32_e32 v4, v17, v4
	v_cvt_pk_bf16_f32 v4, v15, v4
	v_mul_f32_e32 v15, v42, v16
	v_mul_f32_e32 v16, 0xbfb8aa3b, v28
	v_exp_f32_e32 v16, v16
	s_nop 0
	v_add_f32_e32 v16, 1.0, v16
	v_div_scale_f32 v17, s[0:1], v16, v16, v28
	v_rcp_f32_e32 v18, v17
	s_nop 0
	v_fma_f32 v19, -v17, v18, 1.0
	v_fmac_f32_e32 v18, v19, v18
	v_div_scale_f32 v19, vcc, v28, v16, v28
	v_mul_f32_e32 v20, v19, v18
	v_fma_f32 v21, -v17, v20, v19
	v_fmac_f32_e32 v20, v21, v18
	v_fma_f32 v17, -v17, v20, v19
	v_div_fmas_f32 v17, v17, v18, v20
	v_div_fixup_f32 v16, v17, v16, v28
	v_mul_f32_e32 v15, v15, v16
	v_mul_f32_e32 v16, 0xbfb8aa3b, v5
	v_exp_f32_e32 v16, v16
	s_nop 0
	v_add_f32_e32 v16, 1.0, v16
	v_div_scale_f32 v17, s[0:1], v16, v16, v5
	v_rcp_f32_e32 v18, v17
	s_nop 0
	v_fma_f32 v19, -v17, v18, 1.0
	v_fmac_f32_e32 v18, v19, v18
	v_div_scale_f32 v19, vcc, v5, v16, v5
	v_mul_f32_e32 v20, v19, v18
	v_fma_f32 v21, -v17, v20, v19
	v_fmac_f32_e32 v20, v21, v18
	v_fma_f32 v17, -v17, v20, v19
	v_div_fmas_f32 v17, v17, v18, v20
	v_div_fixup_f32 v5, v17, v16, v5
	v_mul_f32_e32 v5, v14, v5
	v_mul_f32_e32 v14, 0xbfb8aa3b, v27
	v_exp_f32_e32 v14, v14
	v_cvt_pk_bf16_f32 v5, v15, v5
	s_nop 0
	v_add_f32_e32 v14, 1.0, v14
	v_div_scale_f32 v15, s[0:1], v14, v14, v27
	v_rcp_f32_e32 v16, v15
	s_nop 0
	v_fma_f32 v17, -v15, v16, 1.0
	v_fmac_f32_e32 v16, v17, v16
	v_div_scale_f32 v17, vcc, v27, v14, v27
	v_mul_f32_e32 v18, v17, v16
	v_fma_f32 v19, -v15, v18, v17
	v_fmac_f32_e32 v18, v19, v16
	v_fma_f32 v15, -v15, v18, v17
	v_div_fmas_f32 v15, v15, v16, v18
	v_div_fixup_f32 v14, v15, v14, v27
	v_mul_f32_e32 v13, v13, v14
	v_mul_f32_e32 v14, 0xbfb8aa3b, v6
	v_exp_f32_e32 v14, v14
	s_nop 0
	v_add_f32_e32 v14, 1.0, v14
	v_div_scale_f32 v15, s[0:1], v14, v14, v6
	v_rcp_f32_e32 v16, v15
	s_nop 0
	v_fma_f32 v17, -v15, v16, 1.0
	v_fmac_f32_e32 v16, v17, v16
	v_div_scale_f32 v17, vcc, v6, v14, v6
	v_mul_f32_e32 v18, v17, v16
	v_fma_f32 v19, -v15, v18, v17
	v_fmac_f32_e32 v18, v19, v16
	v_fma_f32 v15, -v15, v18, v17
	v_div_fmas_f32 v15, v15, v16, v18
	v_div_fixup_f32 v6, v15, v14, v6
	v_mul_f32_e32 v6, v12, v6
	v_mul_f32_e32 v12, 0xbfb8aa3b, v26
	v_exp_f32_e32 v12, v12
	v_cvt_pk_bf16_f32 v6, v13, v6
	s_nop 0
	v_add_f32_e32 v12, 1.0, v12
	v_div_scale_f32 v13, s[0:1], v12, v12, v26
	v_rcp_f32_e32 v14, v13
	s_nop 0
	v_fma_f32 v15, -v13, v14, 1.0
	v_fmac_f32_e32 v14, v15, v14
	v_div_scale_f32 v15, vcc, v26, v12, v26
	v_mul_f32_e32 v16, v15, v14
	v_fma_f32 v17, -v13, v16, v15
	v_fmac_f32_e32 v16, v17, v14
	v_fma_f32 v13, -v13, v16, v15
	v_div_fmas_f32 v13, v13, v14, v16
	v_div_fixup_f32 v12, v13, v12, v26
	v_mul_f32_e32 v11, v11, v12
	v_mul_f32_e32 v12, 0xbfb8aa3b, v7
	v_exp_f32_e32 v12, v12
	s_nop 0
	v_add_f32_e32 v12, 1.0, v12
	v_div_scale_f32 v13, s[0:1], v12, v12, v7
	v_rcp_f32_e32 v14, v13
	s_mov_b64 s[0:1], 0
	v_fma_f32 v15, -v13, v14, 1.0
	v_fmac_f32_e32 v14, v15, v14
	v_div_scale_f32 v15, vcc, v7, v12, v7
	v_mul_f32_e32 v16, v15, v14
	v_fma_f32 v17, -v13, v16, v15
	v_fmac_f32_e32 v16, v17, v14
	v_fma_f32 v13, -v13, v16, v15
	v_div_fmas_f32 v13, v13, v14, v16
	v_div_fixup_f32 v7, v13, v12, v7
	v_mul_f32_e32 v7, v10, v7
	v_cvt_pk_bf16_f32 v7, v11, v7
	global_store_dwordx4 v[8:9], v[0:3], off offset:1024
	global_store_dwordx4 v[8:9], v[4:7], off offset:3072

.LBB0_1100:
	v_lshl_add_u64 v[4:5], v[2:3], 0, v[164:165]
	global_load_dwordx4 v[8:11], v[4:5], off
	global_load_dwordx4 v[48:51], v[4:5], off offset:1024
	v_add_u32_e32 v22, s0, v46
	ds_read_b128 v[12:15], v22
	s_addk_i32 s0, 0x810
	s_cmpk_eq_i32 s0, 0x4080
	s_waitcnt vmcnt(1)
	v_and_b32_e32 v35, 0xffff0000, v8
	s_waitcnt vmcnt(0)
	v_lshlrev_b32_e32 v21, 16, v50
	v_and_b32_e32 v20, 0xffff0000, v50
	v_lshlrev_b32_e32 v17, 16, v51
	v_and_b32_e32 v16, 0xffff0000, v51
	ds_read_b128 v[50:53], v22 offset:1024
	s_waitcnt lgkmcnt(1)
	v_and_b32_e32 v34, 0xffff0000, v12
	v_lshlrev_b32_e32 v37, 16, v8
	v_lshlrev_b32_e32 v36, 16, v12
	v_pk_mul_f32 v[6:7], v[34:35], v[34:35]
	v_lshlrev_b32_e32 v33, 16, v9
	v_pk_fma_f32 v[18:19], v[36:37], v[36:37], v[6:7]
	v_lshlrev_b32_e32 v32, 16, v13
	v_and_b32_e32 v29, 0xffff0000, v9
	v_and_b32_e32 v28, 0xffff0000, v13
	v_lshlrev_b32_e32 v31, 16, v10
	v_and_b32_e32 v27, 0xffff0000, v10
	v_lshlrev_b32_e32 v25, 16, v11
	v_and_b32_e32 v23, 0xffff0000, v11
	v_pk_fma_f32 v[10:11], v[32:33], v[32:33], v[18:19]
	v_lshlrev_b32_e32 v30, 16, v14
	v_pk_fma_f32 v[10:11], v[28:29], v[28:29], v[10:11]
	v_and_b32_e32 v26, 0xffff0000, v14
	v_pk_fma_f32 v[10:11], v[30:31], v[30:31], v[10:11]
	v_lshlrev_b32_e32 v24, 16, v15
	v_pk_fma_f32 v[10:11], v[26:27], v[26:27], v[10:11]
	v_and_b32_e32 v22, 0xffff0000, v15
	v_pk_fma_f32 v[10:11], v[24:25], v[24:25], v[10:11]
	v_lshlrev_b32_e32 v19, 16, v48
	v_pk_fma_f32 v[54:55], v[22:23], v[22:23], v[10:11]
	s_waitcnt lgkmcnt(0)
	v_lshlrev_b32_e32 v18, 16, v50
	v_and_b32_e32 v15, 0xffff0000, v48
	v_and_b32_e32 v14, 0xffff0000, v50
	v_lshlrev_b32_e32 v13, 16, v49
	v_and_b32_e32 v11, 0xffff0000, v49
	v_pk_fma_f32 v[48:49], v[18:19], v[18:19], v[54:55]
	v_lshlrev_b32_e32 v9, 16, v52
	v_and_b32_e32 v8, 0xffff0000, v52
	v_lshlrev_b32_e32 v12, 16, v51
	v_pk_fma_f32 v[48:49], v[14:15], v[14:15], v[48:49]
	v_lshlrev_b32_e32 v7, 16, v53
	v_and_b32_e32 v6, 0xffff0000, v53
	v_pk_mul_f32 v[38:39], v[20:21], v[20:21]
	v_pk_mul_f32 v[52:53], v[8:9], v[8:9]
	v_and_b32_e32 v10, 0xffff0000, v51
	v_pk_fma_f32 v[48:49], v[12:13], v[12:13], v[48:49]
	v_mov_b32_e32 v50, v53
	v_pk_fma_f32 v[48:49], v[10:11], v[10:11], v[48:49]
	v_mov_b32_e32 v51, v39
	v_pk_add_f32 v[48:49], v[50:51], v[48:49]
	v_pk_mul_f32 v[50:51], v[16:17], v[16:17]
	v_pk_mul_f32 v[54:55], v[6:7], v[6:7]
	v_mov_b32_e32 v53, v38
	v_pk_add_f32 v[38:39], v[52:53], v[48:49]
	v_mov_b32_e32 v48, v55
	v_mov_b32_e32 v49, v51
	v_pk_add_f32 v[38:39], v[48:49], v[38:39]
	v_mov_b32_e32 v55, v50
	v_pk_add_f32 v[38:39], v[54:55], v[38:39]
	v_mov_b32_e32 v48, v38
	v_mov_b32_e32 v49, v39
	s_nop 1
	v_permlane32_swap_b32_e32 v38, v48
	v_permlane32_swap_b32_e32 v39, v49
	s_nop 0
	v_add_f32_e32 v38, v38, v48
	v_add_f32_e32 v39, v39, v49
	v_mov_b32_e32 v48, v38
	v_mov_b32_e32 v49, v39
	s_nop 1
	v_permlane16_swap_b32_e32 v38, v48
	v_permlane16_swap_b32_e32 v39, v49
	s_nop 0
	v_add_f32_e32 v38, v38, v48
	v_add_f32_e32 v39, v39, v49
	s_nop 1
	v_add_f32_dpp v38, v38, v38 row_ror:8 row_mask:0xf bank_mask:0xf
	v_add_f32_dpp v39, v39, v39 row_ror:8 row_mask:0xf bank_mask:0xf
	s_nop 1
	v_add_f32_dpp v38, v38, v38 row_ror:4 row_mask:0xf bank_mask:0xf
	v_add_f32_dpp v39, v39, v39 row_ror:4 row_mask:0xf bank_mask:0xf
	s_nop 1
	v_add_f32_dpp v38, v38, v38 row_ror:2 row_mask:0xf bank_mask:0xf
	v_add_f32_dpp v39, v39, v39 row_ror:2 row_mask:0xf bank_mask:0xf
	s_nop 1
	v_add_f32_dpp v38, v38, v38 row_ror:1 row_mask:0xf bank_mask:0xf
	v_add_f32_dpp v39, v39, v39 row_ror:1 row_mask:0xf bank_mask:0xf
	s_nop 1
	s_nop 0
	v_pk_fma_f32 v[38:39], v[38:39], s[20:21], v[166:167] op_sel_hi:[1,0,0]
	s_nop 0
	v_mul_f32_e32 v47, 0x4b800000, v39
	v_cmp_gt_f32_e64 s[10:11], s58, v39
	v_cmp_gt_f32_e32 vcc, s58, v38
	s_nop 0
	v_cndmask_b32_e64 v39, v39, v47, s[10:11]
	v_rsq_f32_e32 v39, v39
	s_nop 0
	v_mul_f32_e32 v47, 0x45800000, v39
	v_cndmask_b32_e64 v48, v39, v47, s[10:11]
	v_mul_f32_e32 v39, 0x4b800000, v38
	v_cndmask_b32_e32 v38, v38, v39, vcc
	v_rsq_f32_e32 v38, v38
	v_mul_f32_e32 v37, v48, v37
	v_mul_f32_e32 v35, v48, v35
	v_mul_f32_e32 v33, v48, v33
	v_mul_f32_e32 v39, 0x45800000, v38
	v_cndmask_b32_e32 v47, v38, v39, vcc
	v_lshl_add_u64 v[38:39], v[0:1], 0, v[164:165]
	global_load_dwordx4 v[50:53], v[38:39], off offset:1664
	v_mul_f32_e32 v29, v48, v29
	v_mul_f32_e32 v27, v48, v27
	v_mul_f32_e32 v25, v48, v25
	v_mul_f32_e32 v23, v48, v23
	v_mul_f32_e32 v22, v47, v22
	v_mul_f32_e32 v19, v48, v19
	v_mul_f32_e32 v15, v48, v15
	v_mul_f32_e32 v13, v48, v13
	v_mul_f32_e32 v11, v48, v11
	v_mul_f32_e32 v10, v47, v10
	v_mul_f32_e32 v9, v47, v9
	v_mul_f32_e32 v8, v47, v8
	v_mul_f32_e32 v7, v47, v7
	v_mul_f32_e32 v6, v47, v6
	s_waitcnt vmcnt(0)
	v_lshlrev_b32_e32 v49, 16, v50
	v_and_b32_e32 v54, 0xffff0000, v50
	v_lshlrev_b32_e32 v55, 16, v51
	v_and_b32_e32 v56, 0xffff0000, v51
	v_lshlrev_b32_e32 v57, 16, v52
	v_and_b32_e32 v58, 0xffff0000, v52
	v_lshlrev_b32_e32 v59, 16, v53
	v_and_b32_e32 v60, 0xffff0000, v53
	global_load_dwordx4 v[50:53], v[38:39], off offset:3712
	s_waitcnt vmcnt(0)
	v_lshlrev_b32_e32 v61, 16, v50
	v_and_b32_e32 v62, 0xffff0000, v50
	v_mul_f32_e32 v50, 0xbfb8aa3b, v49
	v_exp_f32_e32 v50, v50
	v_lshlrev_b32_e32 v63, 16, v51
	v_and_b32_e32 v64, 0xffff0000, v51
	v_lshlrev_b32_e32 v65, 16, v52
	v_add_f32_e32 v50, 1.0, v50
	v_div_scale_f32 v51, s[8:9], v50, v50, v49
	v_and_b32_e32 v66, 0xffff0000, v52
	v_rcp_f32_e32 v52, v51
	v_lshlrev_b32_e32 v67, 16, v53
	v_and_b32_e32 v68, 0xffff0000, v53
	v_fma_f32 v53, -v51, v52, 1.0
	v_fmac_f32_e32 v52, v53, v52
	v_div_scale_f32 v53, vcc, v49, v50, v49
	v_mul_f32_e32 v69, v53, v52
	v_fma_f32 v70, -v51, v69, v53
	v_fmac_f32_e32 v69, v70, v52
	v_fma_f32 v51, -v51, v69, v53
	v_div_fmas_f32 v51, v51, v52, v69
	v_div_fixup_f32 v49, v51, v50, v49
	v_mul_f32_e32 v37, v37, v49
	v_mul_f32_e32 v49, 0xbfb8aa3b, v54
	v_exp_f32_e32 v49, v49
	s_nop 0
	v_add_f32_e32 v49, 1.0, v49
	v_div_scale_f32 v50, s[8:9], v49, v49, v54
	v_rcp_f32_e32 v51, v50
	s_nop 0
	v_fma_f32 v52, -v50, v51, 1.0
	v_fmac_f32_e32 v51, v52, v51
	v_div_scale_f32 v52, vcc, v54, v49, v54
	v_mul_f32_e32 v53, v52, v51
	v_fma_f32 v69, -v50, v53, v52
	v_fmac_f32_e32 v53, v69, v51
	v_fma_f32 v50, -v50, v53, v52
	v_div_fmas_f32 v50, v50, v51, v53
	v_div_fixup_f32 v49, v50, v49, v54
	v_mul_f32_e32 v35, v35, v49
	v_cvt_pk_bf16_f32 v50, v37, v35
	v_mul_f32_e32 v35, 0xbfb8aa3b, v55
	v_exp_f32_e32 v35, v35
	s_nop 0
	v_add_f32_e32 v35, 1.0, v35
	v_div_scale_f32 v37, s[8:9], v35, v35, v55
	v_rcp_f32_e32 v49, v37
	s_nop 0
	v_fma_f32 v51, -v37, v49, 1.0
	v_fmac_f32_e32 v49, v51, v49
	v_div_scale_f32 v51, vcc, v55, v35, v55
	v_mul_f32_e32 v52, v51, v49
	v_fma_f32 v53, -v37, v52, v51
	v_fmac_f32_e32 v52, v53, v49
	v_fma_f32 v37, -v37, v52, v51
	v_div_fmas_f32 v37, v37, v49, v52
	v_div_fixup_f32 v35, v37, v35, v55
	v_mul_f32_e32 v33, v33, v35
	v_mul_f32_e32 v35, 0xbfb8aa3b, v56
	v_exp_f32_e32 v35, v35
	s_nop 0
	v_add_f32_e32 v35, 1.0, v35
	v_div_scale_f32 v37, s[8:9], v35, v35, v56
	v_rcp_f32_e32 v49, v37
	s_nop 0
	v_fma_f32 v51, -v37, v49, 1.0
	v_fmac_f32_e32 v49, v51, v49
	v_div_scale_f32 v51, vcc, v56, v35, v56
	v_mul_f32_e32 v52, v51, v49
	v_fma_f32 v53, -v37, v52, v51
	v_fmac_f32_e32 v52, v53, v49
	v_fma_f32 v37, -v37, v52, v51
	v_div_fmas_f32 v37, v37, v49, v52
	v_div_fixup_f32 v35, v37, v35, v56
	v_mul_f32_e32 v29, v29, v35
	v_cvt_pk_bf16_f32 v51, v33, v29
	v_mul_f32_e32 v29, v48, v31
	v_mul_f32_e32 v31, 0xbfb8aa3b, v57
	v_exp_f32_e32 v31, v31
	s_nop 0
	v_add_f32_e32 v31, 1.0, v31
	v_div_scale_f32 v33, s[8:9], v31, v31, v57
	v_rcp_f32_e32 v35, v33
	s_nop 0
	v_fma_f32 v37, -v33, v35, 1.0
	v_fmac_f32_e32 v35, v37, v35
	v_div_scale_f32 v37, vcc, v57, v31, v57
	v_mul_f32_e32 v49, v37, v35
	v_fma_f32 v52, -v33, v49, v37
	v_fmac_f32_e32 v49, v52, v35
	v_fma_f32 v33, -v33, v49, v37
	v_div_fmas_f32 v33, v33, v35, v49
	v_div_fixup_f32 v31, v33, v31, v57
	v_mul_f32_e32 v29, v29, v31
	v_mul_f32_e32 v31, 0xbfb8aa3b, v58
	v_exp_f32_e32 v31, v31
	s_nop 0
	v_add_f32_e32 v31, 1.0, v31
	v_div_scale_f32 v33, s[8:9], v31, v31, v58
	v_rcp_f32_e32 v35, v33
	s_nop 0
	v_fma_f32 v37, -v33, v35, 1.0
	v_fmac_f32_e32 v35, v37, v35
	v_div_scale_f32 v37, vcc, v58, v31, v58
	v_mul_f32_e32 v49, v37, v35
	v_fma_f32 v52, -v33, v49, v37
	v_fmac_f32_e32 v49, v52, v35
	v_fma_f32 v33, -v33, v49, v37
	v_div_fmas_f32 v33, v33, v35, v49
	v_div_fixup_f32 v31, v33, v31, v58
	v_mul_f32_e32 v27, v27, v31
	v_cvt_pk_bf16_f32 v52, v29, v27
	v_mul_f32_e32 v27, 0xbfb8aa3b, v59
	v_exp_f32_e32 v27, v27
	s_nop 0
	v_add_f32_e32 v27, 1.0, v27
	v_div_scale_f32 v29, s[8:9], v27, v27, v59
	v_rcp_f32_e32 v31, v29
	s_nop 0
	v_fma_f32 v33, -v29, v31, 1.0
	v_fmac_f32_e32 v31, v33, v31
	v_div_scale_f32 v33, vcc, v59, v27, v59
	v_mul_f32_e32 v35, v33, v31
	v_fma_f32 v37, -v29, v35, v33
	v_fmac_f32_e32 v35, v37, v31
	v_fma_f32 v29, -v29, v35, v33
	v_div_fmas_f32 v29, v29, v31, v35
	v_div_fixup_f32 v27, v29, v27, v59
	v_mul_f32_e32 v25, v25, v27
	v_mul_f32_e32 v27, 0xbfb8aa3b, v60
	v_exp_f32_e32 v27, v27
	s_nop 0
	v_add_f32_e32 v27, 1.0, v27
	v_div_scale_f32 v29, s[8:9], v27, v27, v60
	v_rcp_f32_e32 v31, v29
	s_nop 0
	v_fma_f32 v33, -v29, v31, 1.0
	v_fmac_f32_e32 v31, v33, v31
	v_div_scale_f32 v33, vcc, v60, v27, v60
	v_mul_f32_e32 v35, v33, v31
	v_fma_f32 v37, -v29, v35, v33
	v_fmac_f32_e32 v35, v37, v31
	v_fma_f32 v29, -v29, v35, v33
	v_div_fmas_f32 v29, v29, v31, v35
	v_div_fixup_f32 v27, v29, v27, v60
	v_mul_f32_e32 v23, v23, v27
	v_cvt_pk_bf16_f32 v53, v25, v23
	v_mul_f32_e32 v25, 0xbfb8aa3b, v61
	v_exp_f32_e32 v25, v25
	v_mul_f32_e32 v23, v47, v36
	v_add_f32_e32 v25, 1.0, v25
	v_div_scale_f32 v27, s[8:9], v25, v25, v61
	v_rcp_f32_e32 v29, v27
	s_nop 0
	v_fma_f32 v31, -v27, v29, 1.0
	v_fmac_f32_e32 v29, v31, v29
	v_div_scale_f32 v31, vcc, v61, v25, v61
	v_mul_f32_e32 v33, v31, v29
	v_fma_f32 v35, -v27, v33, v31
	v_fmac_f32_e32 v33, v35, v29
	v_fma_f32 v27, -v27, v33, v31
	v_div_fmas_f32 v27, v27, v29, v33
	v_div_fixup_f32 v25, v27, v25, v61
	v_mul_f32_e32 v27, 0xbfb8aa3b, v62
	v_exp_f32_e32 v27, v27
	v_mul_f32_e32 v23, v23, v25
	v_mul_f32_e32 v25, v47, v34
	v_add_f32_e32 v27, 1.0, v27
	v_div_scale_f32 v29, s[8:9], v27, v27, v62
	v_rcp_f32_e32 v31, v29
	s_nop 0
	v_fma_f32 v33, -v29, v31, 1.0
	v_fmac_f32_e32 v31, v33, v31
	v_div_scale_f32 v33, vcc, v62, v27, v62
	v_mul_f32_e32 v34, v33, v31
	v_fma_f32 v35, -v29, v34, v33
	v_fmac_f32_e32 v34, v35, v31
	v_fma_f32 v29, -v29, v34, v33
	v_div_fmas_f32 v29, v29, v31, v34
	v_div_fixup_f32 v27, v29, v27, v62
	v_mul_f32_e32 v25, v25, v27
	v_cvt_pk_bf16_f32 v34, v23, v25
	v_mul_f32_e32 v25, 0xbfb8aa3b, v63
	v_exp_f32_e32 v25, v25
	v_mul_f32_e32 v23, v47, v32
	v_add_f32_e32 v25, 1.0, v25
	v_div_scale_f32 v27, s[8:9], v25, v25, v63
	v_rcp_f32_e32 v29, v27
	s_nop 0
	v_fma_f32 v31, -v27, v29, 1.0
	v_fmac_f32_e32 v29, v31, v29
	v_div_scale_f32 v31, vcc, v63, v25, v63
	v_mul_f32_e32 v32, v31, v29
	v_fma_f32 v33, -v27, v32, v31
	v_fmac_f32_e32 v32, v33, v29
	v_fma_f32 v27, -v27, v32, v31
	v_div_fmas_f32 v27, v27, v29, v32
	v_div_fixup_f32 v25, v27, v25, v63
	v_mul_f32_e32 v27, 0xbfb8aa3b, v64
	v_exp_f32_e32 v27, v27
	v_mul_f32_e32 v23, v23, v25
	v_mul_f32_e32 v25, v47, v28
	v_add_f32_e32 v27, 1.0, v27
	v_div_scale_f32 v28, s[8:9], v27, v27, v64
	v_rcp_f32_e32 v29, v28
	s_nop 0
	v_fma_f32 v31, -v28, v29, 1.0
	v_fmac_f32_e32 v29, v31, v29
	v_div_scale_f32 v31, vcc, v64, v27, v64
	v_mul_f32_e32 v32, v31, v29
	v_fma_f32 v33, -v28, v32, v31
	v_fmac_f32_e32 v32, v33, v29
	v_fma_f32 v28, -v28, v32, v31
	v_div_fmas_f32 v28, v28, v29, v32
	v_div_fixup_f32 v27, v28, v27, v64
	v_mul_f32_e32 v25, v25, v27
	v_cvt_pk_bf16_f32 v35, v23, v25
	v_mul_f32_e32 v25, 0xbfb8aa3b, v65
	v_exp_f32_e32 v25, v25
	v_mul_f32_e32 v23, v47, v30
	v_add_f32_e32 v25, 1.0, v25
	v_div_scale_f32 v27, s[8:9], v25, v25, v65
	v_rcp_f32_e32 v28, v27
	s_nop 0
	v_fma_f32 v29, -v27, v28, 1.0
	v_fmac_f32_e32 v28, v29, v28
	v_div_scale_f32 v29, vcc, v65, v25, v65
	v_mul_f32_e32 v30, v29, v28
	v_fma_f32 v31, -v27, v30, v29
	v_fmac_f32_e32 v30, v31, v28
	v_fma_f32 v27, -v27, v30, v29
	v_div_fmas_f32 v27, v27, v28, v30
	v_div_fixup_f32 v25, v27, v25, v65
	v_mul_f32_e32 v23, v23, v25
	v_mul_f32_e32 v25, v47, v26
	v_mul_f32_e32 v26, 0xbfb8aa3b, v66
	v_exp_f32_e32 v26, v26
	s_nop 0
	v_add_f32_e32 v26, 1.0, v26
	v_div_scale_f32 v27, s[8:9], v26, v26, v66
	v_rcp_f32_e32 v28, v27
	s_nop 0
	v_fma_f32 v29, -v27, v28, 1.0
	v_fmac_f32_e32 v28, v29, v28
	v_div_scale_f32 v29, vcc, v66, v26, v66
	v_mul_f32_e32 v30, v29, v28
	v_fma_f32 v31, -v27, v30, v29
	v_fmac_f32_e32 v30, v31, v28
	v_fma_f32 v27, -v27, v30, v29
	v_div_fmas_f32 v27, v27, v28, v30
	v_div_fixup_f32 v26, v27, v26, v66
	v_mul_f32_e32 v25, v25, v26
	v_cvt_pk_bf16_f32 v36, v23, v25
	v_mul_f32_e32 v23, v47, v24
	v_mul_f32_e32 v24, 0xbfb8aa3b, v67
	v_exp_f32_e32 v24, v24
	s_nop 0
	v_add_f32_e32 v24, 1.0, v24
	v_div_scale_f32 v25, s[8:9], v24, v24, v67
	v_rcp_f32_e32 v26, v25
	s_nop 0
	v_fma_f32 v27, -v25, v26, 1.0
	v_fmac_f32_e32 v26, v27, v26
	v_div_scale_f32 v27, vcc, v67, v24, v67
	v_mul_f32_e32 v28, v27, v26
	v_fma_f32 v29, -v25, v28, v27
	v_fmac_f32_e32 v28, v29, v26
	v_fma_f32 v25, -v25, v28, v27
	v_div_fmas_f32 v25, v25, v26, v28
	v_div_fixup_f32 v24, v25, v24, v67
	v_mul_f32_e32 v23, v23, v24
	v_mul_f32_e32 v24, 0xbfb8aa3b, v68
	v_exp_f32_e32 v24, v24
	s_nop 0
	v_add_f32_e32 v24, 1.0, v24
	v_div_scale_f32 v25, s[8:9], v24, v24, v68
	v_rcp_f32_e32 v26, v25
	s_nop 0
	v_fma_f32 v27, -v25, v26, 1.0
	v_fmac_f32_e32 v26, v27, v26
	v_div_scale_f32 v27, vcc, v68, v24, v68
	v_mul_f32_e32 v28, v27, v26
	v_fma_f32 v29, -v25, v28, v27
	v_fmac_f32_e32 v28, v29, v26
	v_fma_f32 v25, -v25, v28, v27
	v_div_fmas_f32 v25, v25, v26, v28
	v_div_fixup_f32 v24, v25, v24, v68
	v_mul_f32_e32 v22, v22, v24
	v_cvt_pk_bf16_f32 v37, v23, v22
	global_store_dwordx4 v[4:5], v[50:53], off
	global_store_dwordx4 v[4:5], v[34:37], off offset:2048
	global_load_dwordx4 v[22:25], v[38:39], off offset:2688
	s_waitcnt vmcnt(0)
	v_lshlrev_b32_e32 v26, 16, v22
	v_and_b32_e32 v27, 0xffff0000, v22
	v_add_co_u32_e32 v22, vcc, s18, v38
	v_lshlrev_b32_e32 v28, 16, v23
	v_and_b32_e32 v29, 0xffff0000, v23
	v_addc_co_u32_e32 v23, vcc, 0, v39, vcc
	v_lshlrev_b32_e32 v30, 16, v24
	v_and_b32_e32 v31, 0xffff0000, v24
	v_lshlrev_b32_e32 v32, 16, v25
	v_and_b32_e32 v33, 0xffff0000, v25
	global_load_dwordx4 v[22:25], v[22:23], off offset:640
	s_waitcnt vmcnt(0)
	v_lshlrev_b32_e32 v34, 16, v22
	v_and_b32_e32 v35, 0xffff0000, v22
	v_mul_f32_e32 v22, 0xbfb8aa3b, v26
	v_exp_f32_e32 v22, v22
	v_lshlrev_b32_e32 v36, 16, v23
	v_and_b32_e32 v37, 0xffff0000, v23
	v_lshlrev_b32_e32 v38, 16, v24
	v_add_f32_e32 v22, 1.0, v22
	v_div_scale_f32 v23, s[8:9], v22, v22, v26
	v_and_b32_e32 v39, 0xffff0000, v24
	v_rcp_f32_e32 v24, v23
	v_lshlrev_b32_e32 v49, 16, v25
	v_and_b32_e32 v50, 0xffff0000, v25
	v_fma_f32 v25, -v23, v24, 1.0
	v_fmac_f32_e32 v24, v25, v24
	v_div_scale_f32 v25, vcc, v26, v22, v26
	v_mul_f32_e32 v51, v25, v24
	v_fma_f32 v52, -v23, v51, v25
	v_fmac_f32_e32 v51, v52, v24
	v_fma_f32 v23, -v23, v51, v25
	v_div_fmas_f32 v23, v23, v24, v51
	v_div_fixup_f32 v22, v23, v22, v26
	v_mul_f32_e32 v19, v19, v22
	v_mul_f32_e32 v22, 0xbfb8aa3b, v27
	v_exp_f32_e32 v22, v22
	s_nop 0
	v_add_f32_e32 v22, 1.0, v22
	v_div_scale_f32 v23, s[8:9], v22, v22, v27
	v_rcp_f32_e32 v24, v23
	s_nop 0
	v_fma_f32 v25, -v23, v24, 1.0
	v_fmac_f32_e32 v24, v25, v24
	v_div_scale_f32 v25, vcc, v27, v22, v27
	v_mul_f32_e32 v26, v25, v24
	v_fma_f32 v51, -v23, v26, v25
	v_fmac_f32_e32 v26, v51, v24
	v_fma_f32 v23, -v23, v26, v25
	v_div_fmas_f32 v23, v23, v24, v26
	v_div_fixup_f32 v22, v23, v22, v27
	v_mul_f32_e32 v15, v15, v22
	v_cvt_pk_bf16_f32 v22, v19, v15
	v_mul_f32_e32 v15, 0xbfb8aa3b, v28
	v_exp_f32_e32 v15, v15
	s_nop 0
	v_add_f32_e32 v15, 1.0, v15
	v_div_scale_f32 v19, s[8:9], v15, v15, v28
	v_rcp_f32_e32 v23, v19
	s_nop 0
	v_fma_f32 v24, -v19, v23, 1.0
	v_fmac_f32_e32 v23, v24, v23
	v_div_scale_f32 v24, vcc, v28, v15, v28
	v_mul_f32_e32 v25, v24, v23
	v_fma_f32 v26, -v19, v25, v24
	v_fmac_f32_e32 v25, v26, v23
	v_fma_f32 v19, -v19, v25, v24
	v_div_fmas_f32 v19, v19, v23, v25
	v_div_fixup_f32 v15, v19, v15, v28
	v_mul_f32_e32 v13, v13, v15
	v_mul_f32_e32 v15, 0xbfb8aa3b, v29
	v_exp_f32_e32 v15, v15
	s_nop 0
	v_add_f32_e32 v15, 1.0, v15
	v_div_scale_f32 v19, s[8:9], v15, v15, v29
	v_rcp_f32_e32 v23, v19
	s_nop 0
	v_fma_f32 v24, -v19, v23, 1.0
	v_fmac_f32_e32 v23, v24, v23
	v_div_scale_f32 v24, vcc, v29, v15, v29
	v_mul_f32_e32 v25, v24, v23
	v_fma_f32 v26, -v19, v25, v24
	v_fmac_f32_e32 v25, v26, v23
	v_fma_f32 v19, -v19, v25, v24
	v_div_fmas_f32 v19, v19, v23, v25
	v_div_fixup_f32 v15, v19, v15, v29
	v_mul_f32_e32 v11, v11, v15
	v_cvt_pk_bf16_f32 v23, v13, v11
	v_mul_f32_e32 v13, 0xbfb8aa3b, v30
	v_exp_f32_e32 v13, v13
	v_mul_f32_e32 v11, v48, v21
	v_add_f32_e32 v13, 1.0, v13
	v_div_scale_f32 v15, s[8:9], v13, v13, v30
	v_rcp_f32_e32 v19, v15
	s_nop 0
	v_fma_f32 v21, -v15, v19, 1.0
	v_fmac_f32_e32 v19, v21, v19
	v_div_scale_f32 v21, vcc, v30, v13, v30
	v_mul_f32_e32 v24, v21, v19
	v_fma_f32 v25, -v15, v24, v21
	v_fmac_f32_e32 v24, v25, v19
	v_fma_f32 v15, -v15, v24, v21
	v_div_fmas_f32 v15, v15, v19, v24
	v_div_fixup_f32 v13, v15, v13, v30
	v_mul_f32_e32 v15, 0xbfb8aa3b, v31
	v_exp_f32_e32 v15, v15
	v_mul_f32_e32 v11, v11, v13
	v_mul_f32_e32 v13, v48, v20
	v_add_f32_e32 v15, 1.0, v15
	v_div_scale_f32 v19, s[8:9], v15, v15, v31
	v_rcp_f32_e32 v20, v19
	s_nop 0
	v_fma_f32 v21, -v19, v20, 1.0
	v_fmac_f32_e32 v20, v21, v20
	v_div_scale_f32 v21, vcc, v31, v15, v31
	v_mul_f32_e32 v24, v21, v20
	v_fma_f32 v25, -v19, v24, v21
	v_fmac_f32_e32 v24, v25, v20
	v_fma_f32 v19, -v19, v24, v21
	v_div_fmas_f32 v19, v19, v20, v24
	v_div_fixup_f32 v15, v19, v15, v31
	v_mul_f32_e32 v13, v13, v15
	v_cvt_pk_bf16_f32 v24, v11, v13
	v_mul_f32_e32 v13, 0xbfb8aa3b, v32
	v_exp_f32_e32 v13, v13
	v_mul_f32_e32 v11, v48, v17
	v_add_f32_e32 v13, 1.0, v13
	v_div_scale_f32 v15, s[8:9], v13, v13, v32
	v_rcp_f32_e32 v17, v15
	s_nop 0
	v_fma_f32 v19, -v15, v17, 1.0
	v_fmac_f32_e32 v17, v19, v17
	v_div_scale_f32 v19, vcc, v32, v13, v32
	v_mul_f32_e32 v20, v19, v17
	v_fma_f32 v21, -v15, v20, v19
	v_fmac_f32_e32 v20, v21, v17
	v_fma_f32 v15, -v15, v20, v19
	v_div_fmas_f32 v15, v15, v17, v20
	v_div_fixup_f32 v13, v15, v13, v32
	v_mul_f32_e32 v15, 0xbfb8aa3b, v33
	v_exp_f32_e32 v15, v15
	v_mul_f32_e32 v11, v11, v13
	v_mul_f32_e32 v13, v48, v16
	v_add_f32_e32 v15, 1.0, v15
	v_div_scale_f32 v16, s[8:9], v15, v15, v33
	v_rcp_f32_e32 v17, v16
	s_nop 0
	v_fma_f32 v19, -v16, v17, 1.0
	v_fmac_f32_e32 v17, v19, v17
	v_div_scale_f32 v19, vcc, v33, v15, v33
	v_mul_f32_e32 v20, v19, v17
	v_fma_f32 v21, -v16, v20, v19
	v_fmac_f32_e32 v20, v21, v17
	v_fma_f32 v16, -v16, v20, v19
	v_div_fmas_f32 v16, v16, v17, v20
	v_div_fixup_f32 v15, v16, v15, v33
	v_mul_f32_e32 v13, v13, v15
	v_cvt_pk_bf16_f32 v25, v11, v13
	v_mul_f32_e32 v13, 0xbfb8aa3b, v34
	v_exp_f32_e32 v13, v13
	v_mul_f32_e32 v11, v47, v18
	v_add_f32_e32 v13, 1.0, v13
	v_div_scale_f32 v15, s[8:9], v13, v13, v34
	v_rcp_f32_e32 v16, v15
	s_nop 0
	v_fma_f32 v17, -v15, v16, 1.0
	v_fmac_f32_e32 v16, v17, v16
	v_div_scale_f32 v17, vcc, v34, v13, v34
	v_mul_f32_e32 v18, v17, v16
	v_fma_f32 v19, -v15, v18, v17
	v_fmac_f32_e32 v18, v19, v16
	v_fma_f32 v15, -v15, v18, v17
	v_div_fmas_f32 v15, v15, v16, v18
	v_div_fixup_f32 v13, v15, v13, v34
	v_mul_f32_e32 v11, v11, v13
	v_mul_f32_e32 v13, v47, v14
	v_mul_f32_e32 v14, 0xbfb8aa3b, v35
	v_exp_f32_e32 v14, v14
	s_nop 0
	v_add_f32_e32 v14, 1.0, v14
	v_div_scale_f32 v15, s[8:9], v14, v14, v35
	v_rcp_f32_e32 v16, v15
	s_nop 0
	v_fma_f32 v17, -v15, v16, 1.0
	v_fmac_f32_e32 v16, v17, v16
	v_div_scale_f32 v17, vcc, v35, v14, v35
	v_mul_f32_e32 v18, v17, v16
	v_fma_f32 v19, -v15, v18, v17
	v_fmac_f32_e32 v18, v19, v16
	v_fma_f32 v15, -v15, v18, v17
	v_div_fmas_f32 v15, v15, v16, v18
	v_div_fixup_f32 v14, v15, v14, v35
	v_mul_f32_e32 v13, v13, v14
	v_cvt_pk_bf16_f32 v14, v11, v13
	v_mul_f32_e32 v11, v47, v12
	v_mul_f32_e32 v12, 0xbfb8aa3b, v36
	v_exp_f32_e32 v12, v12
	s_nop 0
	v_add_f32_e32 v12, 1.0, v12
	v_div_scale_f32 v13, s[8:9], v12, v12, v36
	v_rcp_f32_e32 v15, v13
	s_nop 0
	v_fma_f32 v16, -v13, v15, 1.0
	v_fmac_f32_e32 v15, v16, v15
	v_div_scale_f32 v16, vcc, v36, v12, v36
	v_mul_f32_e32 v17, v16, v15
	v_fma_f32 v18, -v13, v17, v16
	v_fmac_f32_e32 v17, v18, v15
	v_fma_f32 v13, -v13, v17, v16
	v_div_fmas_f32 v13, v13, v15, v17
	v_div_fixup_f32 v12, v13, v12, v36
	v_mul_f32_e32 v11, v11, v12
	v_mul_f32_e32 v12, 0xbfb8aa3b, v37
	v_exp_f32_e32 v12, v12
	s_nop 0
	v_add_f32_e32 v12, 1.0, v12
	v_div_scale_f32 v13, s[8:9], v12, v12, v37
	v_rcp_f32_e32 v15, v13
	s_nop 0
	v_fma_f32 v16, -v13, v15, 1.0
	v_fmac_f32_e32 v15, v16, v15
	v_div_scale_f32 v16, vcc, v37, v12, v37
	v_mul_f32_e32 v17, v16, v15
	v_fma_f32 v18, -v13, v17, v16
	v_fmac_f32_e32 v17, v18, v15
	v_fma_f32 v13, -v13, v17, v16
	v_div_fmas_f32 v13, v13, v15, v17
	v_div_fixup_f32 v12, v13, v12, v37
	v_mul_f32_e32 v10, v10, v12
	v_cvt_pk_bf16_f32 v15, v11, v10
	v_mul_f32_e32 v10, 0xbfb8aa3b, v38
	v_exp_f32_e32 v10, v10
	s_nop 0
	v_add_f32_e32 v10, 1.0, v10
	v_div_scale_f32 v11, s[8:9], v10, v10, v38
	v_rcp_f32_e32 v12, v11
	s_nop 0
	v_fma_f32 v13, -v11, v12, 1.0
	v_fmac_f32_e32 v12, v13, v12
	v_div_scale_f32 v13, vcc, v38, v10, v38
	v_mul_f32_e32 v16, v13, v12
	v_fma_f32 v17, -v11, v16, v13
	v_fmac_f32_e32 v16, v17, v12
	v_fma_f32 v11, -v11, v16, v13
	v_div_fmas_f32 v11, v11, v12, v16
	v_div_fixup_f32 v10, v11, v10, v38
	v_mul_f32_e32 v9, v9, v10
	v_mul_f32_e32 v10, 0xbfb8aa3b, v39
	v_exp_f32_e32 v10, v10
	s_nop 0
	v_add_f32_e32 v10, 1.0, v10
	v_div_scale_f32 v11, s[8:9], v10, v10, v39
	v_rcp_f32_e32 v12, v11
	s_nop 0
	v_fma_f32 v13, -v11, v12, 1.0
	v_fmac_f32_e32 v12, v13, v12
	v_div_scale_f32 v13, vcc, v39, v10, v39
	v_mul_f32_e32 v16, v13, v12
	v_fma_f32 v17, -v11, v16, v13
	v_fmac_f32_e32 v16, v17, v12
	v_fma_f32 v11, -v11, v16, v13
	v_div_fmas_f32 v11, v11, v12, v16
	v_div_fixup_f32 v10, v11, v10, v39
	v_mul_f32_e32 v8, v8, v10
	v_cvt_pk_bf16_f32 v16, v9, v8
	v_mul_f32_e32 v8, 0xbfb8aa3b, v49
	v_exp_f32_e32 v8, v8
	s_nop 0
	v_add_f32_e32 v8, 1.0, v8
	v_div_scale_f32 v9, s[8:9], v8, v8, v49
	v_rcp_f32_e32 v10, v9
	s_nop 0
	v_fma_f32 v11, -v9, v10, 1.0
	v_fmac_f32_e32 v10, v11, v10
	v_div_scale_f32 v11, vcc, v49, v8, v49
	v_mul_f32_e32 v12, v11, v10
	v_fma_f32 v13, -v9, v12, v11
	v_fmac_f32_e32 v12, v13, v10
	v_fma_f32 v9, -v9, v12, v11
	v_div_fmas_f32 v9, v9, v10, v12
	v_div_fixup_f32 v8, v9, v8, v49
	v_mul_f32_e32 v7, v7, v8
	v_mul_f32_e32 v8, 0xbfb8aa3b, v50
	v_exp_f32_e32 v8, v8
	s_nop 0
	v_add_f32_e32 v8, 1.0, v8
	v_div_scale_f32 v9, s[8:9], v8, v8, v50
	v_rcp_f32_e32 v10, v9
	s_mov_b64 s[8:9], 0x1700
	v_lshl_add_u64 v[0:1], v[0:1], 0, s[8:9]
	s_mov_b64 s[8:9], 0x1000
	v_fma_f32 v11, -v9, v10, 1.0
	v_fmac_f32_e32 v10, v11, v10
	v_div_scale_f32 v11, vcc, v50, v8, v50
	v_mul_f32_e32 v12, v11, v10
	v_fma_f32 v13, -v9, v12, v11
	v_fmac_f32_e32 v12, v13, v10
	v_fma_f32 v9, -v9, v12, v11
	v_div_fmas_f32 v9, v9, v10, v12
	v_div_fixup_f32 v8, v9, v8, v50
	v_lshl_add_u64 v[2:3], v[2:3], 0, s[8:9]
	v_mul_f32_e32 v6, v6, v8
	v_cvt_pk_bf16_f32 v17, v7, v6
	global_store_dwordx4 v[4:5], v[22:25], off offset:1024
	global_store_dwordx4 v[4:5], v[14:17], off offset:3072
	s_cbranch_scc0 .LBB0_1100
	v_readfirstlane_b32 s8, v167
	s_mov_b64 s[10:11], exec
	v_readlane_b32 s0, v254, 48
	v_readlane_b32 s1, v254, 49
	s_and_b64 s[0:1], s[10:11], s[0:1]
	s_mov_b64 exec, s[0:1]
	s_cbranch_execz .LBB0_1086
	s_mov_b64 s[0:1], exec
	s_lshr_b32 s8, s8, 4
	s_and_b32 s8, s8, 0xffffff0
	v_mbcnt_lo_u32_b32 v0, s0, 0
	s_add_i32 s20, s8, 0
	v_mbcnt_hi_u32_b32 v0, s1, v0
	s_add_i32 s20, s20, 0x220c0
	v_cmp_eq_u32_e32 vcc, 0, v0
	s_and_saveexec_b64 s[8:9], vcc
	s_bcnt1_i32_b64 s0, s[0:1]
	v_mov_b32_e32 v1, s20
	v_mov_b32_e32 v2, s0
	ds_add_rtn_u32 v1, v1, v2
	s_or_b64 exec, exec, s[8:9]
	s_waitcnt lgkmcnt(0)
	v_readfirstlane_b32 s0, v1
	v_mov_b32_e32 v1, s20
	ds_read_b32 v1, v1
	v_add_u32_e32 v0, s0, v0
	v_bitop3_b32 v0, v0, -4, v0 bitop3:0xc
	s_waitcnt lgkmcnt(0)
	v_add_u32_e32 v1, v0, v1
	v_cmp_gt_i32_e32 vcc, 0, v1
	s_and_b64 exec, exec, vcc
	s_cbranch_execz .LBB0_1086
	s_mov_b64 s[0:1], 0
